# counted-wait move: leading wave-half defers its vmcnt(8) from before the pre-compute barrier to the end of the compute segment (one barrier of slack), 5 large GEMM loops
# baseline (speedup 1.0000x reference)
; #define PG8_STAGE(bufoff, gbase, voff) do { _Pragma("unroll") for (int _i = 0; _i < 2; ++_i) { \
;         const unsigned _m0 = ldsu + (unsigned)(bufoff) + ldsw + (unsigned)(_i * 8192); \
;         asm volatile("s_mov_b32 m0, %2\n\ts_nop 0\n\tglobal_load_lds_dwordx4 %0, %1" :: "v"((voff)[_i]), "s"((const char*)(gbase)), "s"(_m0) : "memory"); } } while (0)
; #define PG8_LDA(dst, b, h) do { _Pragma("unroll") for (int m = 0; m < 4; ++m) _Pragma("unroll") for (int k = 0; k < 2; ++k) dst[m][k] = *(const LAS bf16x8*)(lds + PG8_SA(b, h) + aoff + m * 2048 + k * 1024); } while (0)
; #define PG8_LDB(dst, b, h) do { _Pragma("unroll") for (int n = 0; n < 2; ++n) _Pragma("unroll") for (int k = 0; k < 2; ++k) dst[n][k] = *(const LAS bf16x8*)(lds + bbase[b][h] + n * 2048 + k * 1024); } while (0)
; #define PG8_WAIT_V(n) asm volatile("s_waitcnt vmcnt(" #n ")" ::: "memory")
; #define PG8_WAIT_L(n) asm volatile("s_waitcnt lgkmcnt(" #n ")" ::: "memory")
; #define PG8_BAR __builtin_amdgcn_s_barrier()
; #define PG8_SCHED __builtin_amdgcn_sched_barrier(0)
; template <class Epi>
; __device__ __forceinline__ void gemm_phase(LAS unsigned char* lds, const Gemm g, const StaticOrder& S, const Epi& E) {
;     ...
;             PG8_LDB(B0, 0, 0); PG8_SCHED; PG8_LDA(At, 0, 0); PG8_LDA(At2, 0, 1); PG8_STAGE(PG8_SB(1, 1), b1 + hstepB, voffB);
;             PG8_WAIT_V(8); PG8_WAIT_L(0); PG8_BAR; PG8_MMA2B(0, At, At2, B0); PG8_BAR; PG8_SCHED;
.LBB0_233:
	ds_read_b128 v[130:133], v142
	ds_read_b128 v[148:151], v142 offset:1024
	ds_read_b128 v[152:155], v142 offset:2048
	ds_read_b128 v[156:159], v142 offset:3072
	s_add_u32 s8, s4, 0x100
	s_addc_u32 s9, s5, 0
	s_cmp_eq_u32 s62, 12
	s_cselect_b32 s10, s58, s60
	s_cselect_b32 s11, s15, s61
	s_cselect_b32 s80, s59, s8
	s_cselect_b32 s81, s13, s9
	s_add_u32 s38, s10, 0x80
	s_addc_u32 s39, s11, 0
	ds_read_b128 v[166:169], v143
	ds_read_b128 v[178:181], v143 offset:1024
	ds_read_b128 v[182:185], v143 offset:2048
	ds_read_b128 v[186:189], v143 offset:3072
	ds_read_b128 v[190:193], v143 offset:4096
	ds_read_b128 v[194:197], v143 offset:5120
	ds_read_b128 v[198:201], v143 offset:6144
	ds_read_b128 v[202:205], v143 offset:7168
	ds_read_b128 v[214:217], v143 offset:16384
	ds_read_b128 v[218:221], v143 offset:17408
	ds_read_b128 v[222:225], v143 offset:18432
	ds_read_b128 v[226:229], v143 offset:19456
	ds_read_b128 v[230:233], v143 offset:20480
	ds_read_b128 v[234:237], v143 offset:21504
	ds_read_b128 v[238:241], v143 offset:22528
	ds_read_b128 v[242:245], v143 offset:23552
	s_add_u32 s4, s4, 0x40080
	s_addc_u32 s5, s5, 0
	s_mov_b32 m0, s84
	s_nop 0
	global_load_lds_dwordx4 v137, s[4:5]
	s_mov_b32 m0, s85
	s_nop 0
	global_load_lds_dwordx4 v139, s[4:5]
	s_cmp_lg_u64 s[2:3], 0
	s_cbranch_scc1 .Lv8a_0
	s_waitcnt vmcnt(8)
.Lv8a_0:
	s_waitcnt lgkmcnt(0)
	s_barrier
	s_waitcnt lgkmcnt(14)
	v_mfma_f32_16x16x32_bf16 v[124:127], v[130:133], v[166:169], v[124:127]
	v_mfma_f32_16x16x32_bf16 v[120:123], v[152:155], v[166:169], v[120:123]
	s_waitcnt lgkmcnt(13)
	v_mfma_f32_16x16x32_bf16 v[108:111], v[130:133], v[182:185], v[108:111]
	v_mfma_f32_16x16x32_bf16 v[104:107], v[152:155], v[182:185], v[104:107]
	s_waitcnt lgkmcnt(11)
	v_mfma_f32_16x16x32_bf16 v[92:95], v[130:133], v[190:193], v[92:95]
	v_mfma_f32_16x16x32_bf16 v[88:91], v[152:155], v[190:193], v[88:91]
	s_waitcnt lgkmcnt(9)
	v_mfma_f32_16x16x32_bf16 v[76:79], v[130:133], v[198:201], v[76:79]
	v_mfma_f32_16x16x32_bf16 v[72:75], v[152:155], v[198:201], v[72:75]
	s_waitcnt lgkmcnt(7)
	v_mfma_f32_16x16x32_bf16 v[60:63], v[130:133], v[214:217], v[60:63]
	v_mfma_f32_16x16x32_bf16 v[56:59], v[152:155], v[214:217], v[56:59]
	s_waitcnt lgkmcnt(5)
	v_mfma_f32_16x16x32_bf16 v[44:47], v[130:133], v[222:225], v[44:47]
	v_mfma_f32_16x16x32_bf16 v[40:43], v[152:155], v[222:225], v[40:43]
	s_waitcnt lgkmcnt(3)
	v_mfma_f32_16x16x32_bf16 v[28:31], v[130:133], v[230:233], v[28:31]
	v_mfma_f32_16x16x32_bf16 v[24:27], v[152:155], v[230:233], v[24:27]
	s_waitcnt lgkmcnt(1)
	v_mfma_f32_16x16x32_bf16 v[12:15], v[130:133], v[238:241], v[12:15]
	v_mfma_f32_16x16x32_bf16 v[8:11], v[152:155], v[238:241], v[8:11]
	v_mfma_f32_16x16x32_bf16 v[124:127], v[148:151], v[178:181], v[124:127]
	v_mfma_f32_16x16x32_bf16 v[120:123], v[156:159], v[178:181], v[120:123]
	v_mfma_f32_16x16x32_bf16 v[108:111], v[148:151], v[186:189], v[108:111]
	v_mfma_f32_16x16x32_bf16 v[104:107], v[156:159], v[186:189], v[104:107]
	v_mfma_f32_16x16x32_bf16 v[92:95], v[148:151], v[194:197], v[92:95]
	v_mfma_f32_16x16x32_bf16 v[88:91], v[156:159], v[194:197], v[88:91]
	v_mfma_f32_16x16x32_bf16 v[76:79], v[148:151], v[202:205], v[76:79]
	v_mfma_f32_16x16x32_bf16 v[72:75], v[156:159], v[202:205], v[72:75]
	v_mfma_f32_16x16x32_bf16 v[60:63], v[148:151], v[218:221], v[60:63]
	v_mfma_f32_16x16x32_bf16 v[56:59], v[156:159], v[218:221], v[56:59]
	v_mfma_f32_16x16x32_bf16 v[44:47], v[148:151], v[226:229], v[44:47]
	v_mfma_f32_16x16x32_bf16 v[40:43], v[156:159], v[226:229], v[40:43]
	v_mfma_f32_16x16x32_bf16 v[28:31], v[148:151], v[234:237], v[28:31]
	v_mfma_f32_16x16x32_bf16 v[24:27], v[156:159], v[234:237], v[24:27]
	s_waitcnt lgkmcnt(0)
	v_mfma_f32_16x16x32_bf16 v[12:15], v[148:151], v[242:245], v[12:15]
	v_mfma_f32_16x16x32_bf16 v[8:11], v[156:159], v[242:245], v[8:11]
	s_cmp_eq_u64 s[2:3], 0
	s_cbranch_scc1 .Lv8b_0
	s_waitcnt vmcnt(8)
; #define PG8_STAGE(bufoff, gbase, voff) do { _Pragma("unroll") for (int _i = 0; _i < 2; ++_i) { \
;         const unsigned _m0 = ldsu + (unsigned)(bufoff) + ldsw + (unsigned)(_i * 8192); \
;         asm volatile("s_mov_b32 m0, %2\n\ts_nop 0\n\tglobal_load_lds_dwordx4 %0, %1" :: "v"((voff)[_i]), "s"((const char*)(gbase)), "s"(_m0) : "memory"); } } while (0)
; #define PG8_LDA(dst, b, h) do { _Pragma("unroll") for (int m = 0; m < 4; ++m) _Pragma("unroll") for (int k = 0; k < 2; ++k) dst[m][k] = *(const LAS bf16x8*)(lds + PG8_SA(b, h) + aoff + m * 2048 + k * 1024); } while (0)
; #define PG8_LDB(dst, b, h) do { _Pragma("unroll") for (int n = 0; n < 2; ++n) _Pragma("unroll") for (int k = 0; k < 2; ++k) dst[n][k] = *(const LAS bf16x8*)(lds + bbase[b][h] + n * 2048 + k * 1024); } while (0)
; #define PG8_WAIT_V(n) asm volatile("s_waitcnt vmcnt(" #n ")" ::: "memory")
; #define PG8_WAIT_L(n) asm volatile("s_waitcnt lgkmcnt(" #n ")" ::: "memory")
; #define PG8_BAR __builtin_amdgcn_s_barrier()
; #define PG8_SCHED __builtin_amdgcn_sched_barrier(0)
; template <class Epi>
; __device__ __forceinline__ void gemm_phase(LAS unsigned char* lds, const Gemm g, const StaticOrder& S, const Epi& E) {
;     ...
;             PG8_WAIT_V(8); PG8_WAIT_L(0); PG8_BAR; PG8_MMA2B(0, At, At2, B0); PG8_BAR; PG8_SCHED;
;             PG8_LDB(B0, 0, 1); PG8_STAGE(PG8_SB(0, 0), b2, voffB); PG8_STAGE(PG8_SA(0, 0), a2, voffA); PG8_STAGE(PG8_SA(0, 1), a2 + hstepA, voffA);
;             PG8_WAIT_V(8); PG8_WAIT_L(0); PG8_BAR; PG8_MMA2B(1, At, At2, B0); PG8_BAR; PG8_SCHED;
;             PG8_LDB(B0, 1, 0); PG8_SCHED; PG8_LDA(At, 1, 0); PG8_LDA(At2, 1, 1); PG8_STAGE(PG8_SB(0, 1), b2 + hstepB, voffB);
;             PG8_WAIT_V(8); PG8_WAIT_L(0); PG8_BAR; PG8_MMA2B(0, At, At2, B0); PG8_BAR; PG8_SCHED;
.Lv8b_0:
	s_barrier
	ds_read_b128 v[130:133], v144
	ds_read_b128 v[148:151], v144 offset:1024
	ds_read_b128 v[152:155], v144 offset:2048
	ds_read_b128 v[156:159], v144 offset:3072
	s_mov_b32 m0, s29
	s_nop 0
	global_load_lds_dwordx4 v137, s[80:81]
	s_mov_b32 m0, s37
	s_nop 0
	global_load_lds_dwordx4 v139, s[80:81]
	s_mov_b32 m0, s28
	s_nop 0
	global_load_lds_dwordx4 v136, s[10:11]
	s_mov_b32 m0, s47
	s_nop 0
	global_load_lds_dwordx4 v138, s[10:11]
	s_add_u32 s4, s10, 0x40000
	s_addc_u32 s5, s11, 0
	s_mov_b32 m0, s48
	s_nop 0
	global_load_lds_dwordx4 v136, s[4:5]
	s_mov_b32 m0, s49
	s_nop 0
	global_load_lds_dwordx4 v138, s[4:5]
	s_cmp_lg_u64 s[2:3], 0
	s_cbranch_scc1 .Lv8a_1
	s_waitcnt vmcnt(8)
.Lv8a_1:
	s_waitcnt lgkmcnt(0)
	s_barrier
	s_waitcnt lgkmcnt(3)
	v_mfma_f32_16x16x32_bf16 v[116:119], v[130:133], v[166:169], v[116:119]
	s_waitcnt lgkmcnt(1)
	v_mfma_f32_16x16x32_bf16 v[112:115], v[152:155], v[166:169], v[112:115]
	v_mfma_f32_16x16x32_bf16 v[100:103], v[130:133], v[182:185], v[100:103]
	v_mfma_f32_16x16x32_bf16 v[96:99], v[152:155], v[182:185], v[96:99]
	v_mfma_f32_16x16x32_bf16 v[84:87], v[130:133], v[190:193], v[84:87]
	v_mfma_f32_16x16x32_bf16 v[80:83], v[152:155], v[190:193], v[80:83]
	v_mfma_f32_16x16x32_bf16 v[68:71], v[130:133], v[198:201], v[68:71]
	v_mfma_f32_16x16x32_bf16 v[64:67], v[152:155], v[198:201], v[64:67]
	v_mfma_f32_16x16x32_bf16 v[52:55], v[130:133], v[214:217], v[52:55]
	v_mfma_f32_16x16x32_bf16 v[48:51], v[152:155], v[214:217], v[48:51]
	v_mfma_f32_16x16x32_bf16 v[36:39], v[130:133], v[222:225], v[36:39]
	v_mfma_f32_16x16x32_bf16 v[32:35], v[152:155], v[222:225], v[32:35]
	v_mfma_f32_16x16x32_bf16 v[20:23], v[130:133], v[230:233], v[20:23]
	v_mfma_f32_16x16x32_bf16 v[16:19], v[152:155], v[230:233], v[16:19]
	v_mfma_f32_16x16x32_bf16 v[4:7], v[130:133], v[238:241], v[4:7]
	v_mfma_f32_16x16x32_bf16 v[0:3], v[152:155], v[238:241], v[0:3]
	v_mfma_f32_16x16x32_bf16 v[116:119], v[148:151], v[178:181], v[116:119]
	s_waitcnt lgkmcnt(0)
	v_mfma_f32_16x16x32_bf16 v[112:115], v[156:159], v[178:181], v[112:115]
	v_mfma_f32_16x16x32_bf16 v[100:103], v[148:151], v[186:189], v[100:103]
	v_mfma_f32_16x16x32_bf16 v[96:99], v[156:159], v[186:189], v[96:99]
	v_mfma_f32_16x16x32_bf16 v[84:87], v[148:151], v[194:197], v[84:87]
	v_mfma_f32_16x16x32_bf16 v[80:83], v[156:159], v[194:197], v[80:83]
	v_mfma_f32_16x16x32_bf16 v[68:71], v[148:151], v[202:205], v[68:71]
	v_mfma_f32_16x16x32_bf16 v[64:67], v[156:159], v[202:205], v[64:67]
	v_mfma_f32_16x16x32_bf16 v[52:55], v[148:151], v[218:221], v[52:55]
	v_mfma_f32_16x16x32_bf16 v[48:51], v[156:159], v[218:221], v[48:51]
	v_mfma_f32_16x16x32_bf16 v[36:39], v[148:151], v[226:229], v[36:39]
	v_mfma_f32_16x16x32_bf16 v[32:35], v[156:159], v[226:229], v[32:35]
	v_mfma_f32_16x16x32_bf16 v[20:23], v[148:151], v[234:237], v[20:23]
	v_mfma_f32_16x16x32_bf16 v[16:19], v[156:159], v[234:237], v[16:19]
	v_mfma_f32_16x16x32_bf16 v[4:7], v[148:151], v[242:245], v[4:7]
	v_mfma_f32_16x16x32_bf16 v[0:3], v[156:159], v[242:245], v[0:3]
	s_cmp_eq_u64 s[2:3], 0
	s_cbranch_scc1 .Lv8b_1
	s_waitcnt vmcnt(8)
.Lv8b_1:
	s_barrier
	ds_read_b128 v[130:133], v145
	ds_read_b128 v[148:151], v145 offset:1024
	ds_read_b128 v[152:155], v145 offset:2048
	ds_read_b128 v[156:159], v145 offset:3072
	ds_read_b128 v[166:169], v143 offset:32768
	ds_read_b128 v[178:181], v143 offset:33792
	ds_read_b128 v[182:185], v143 offset:34816
	ds_read_b128 v[186:189], v143 offset:35840
	ds_read_b128 v[190:193], v143 offset:36864
	ds_read_b128 v[194:197], v143 offset:37888
	ds_read_b128 v[198:201], v143 offset:38912
	ds_read_b128 v[202:205], v143 offset:39936
	ds_read_b128 v[214:217], v143 offset:49152
	ds_read_b128 v[218:221], v143 offset:50176
	ds_read_b128 v[222:225], v143 offset:51200
	ds_read_b128 v[226:229], v143 offset:52224
	ds_read_b128 v[230:233], v143 offset:53248
	ds_read_b128 v[234:237], v143 offset:54272
	ds_read_b128 v[238:241], v143 offset:55296
	ds_read_b128 v[242:245], v143 offset:56320
	s_add_u32 s4, s80, 0x40000
	s_addc_u32 s5, s81, 0
	s_mov_b32 m0, s50
	s_nop 0
	global_load_lds_dwordx4 v137, s[4:5]
	s_mov_b32 m0, s51
	s_nop 0
	global_load_lds_dwordx4 v139, s[4:5]
	s_cmp_lg_u64 s[2:3], 0
	s_cbranch_scc1 .Lv8a_2
	s_waitcnt vmcnt(8)

; #define PG8_STAGE(bufoff, gbase, voff) do { _Pragma("unroll") for (int _i = 0; _i < 2; ++_i) { \
;         const unsigned _m0 = ldsu + (unsigned)(bufoff) + ldsw + (unsigned)(_i * 8192); \
;         asm volatile("s_mov_b32 m0, %2\n\ts_nop 0\n\tglobal_load_lds_dwordx4 %0, %1" :: "v"((voff)[_i]), "s"((const char*)(gbase)), "s"(_m0) : "memory"); } } while (0)
; #define PG8_LDB(dst, b, h) do { _Pragma("unroll") for (int n = 0; n < 2; ++n) _Pragma("unroll") for (int k = 0; k < 2; ++k) dst[n][k] = *(const LAS bf16x8*)(lds + bbase[b][h] + n * 2048 + k * 1024); } while (0)
; template <class Epi>
; __device__ __forceinline__ void gemm_phase(LAS unsigned char* lds, const Gemm g, const StaticOrder& S, const Epi& E) {
;     ...
;             PG8_LDB(B0, 1, 1); PG8_STAGE(PG8_SB(1, 0), b3, voffB); PG8_STAGE(PG8_SA(1, 0), a3, voffA); PG8_STAGE(PG8_SA(1, 1), a3 + hstepA, voffA);
.Lv8b_2:
	s_barrier
	s_add_u32 s4, s80, 0x80
	ds_read_b128 v[130:133], v146
	ds_read_b128 v[148:151], v146 offset:1024
	ds_read_b128 v[152:155], v146 offset:2048
	ds_read_b128 v[156:159], v146 offset:3072
	s_addc_u32 s5, s81, 0
	s_mov_b32 m0, s52
	s_nop 0
	global_load_lds_dwordx4 v137, s[4:5]
	s_mov_b32 m0, s53
	s_nop 0
	global_load_lds_dwordx4 v139, s[4:5]
	s_mov_b32 m0, s54
	s_nop 0
	global_load_lds_dwordx4 v136, s[38:39]
	s_mov_b32 m0, s55
	s_nop 0
	global_load_lds_dwordx4 v138, s[38:39]
	s_add_u32 s4, s10, 0x40080
	s_addc_u32 s5, s11, 0
	s_mov_b32 m0, s82
	s_nop 0
	global_load_lds_dwordx4 v136, s[4:5]
	s_mov_b32 m0, s83
	s_nop 0
	global_load_lds_dwordx4 v138, s[4:5]
	s_cmp_lg_u64 s[2:3], 0
	s_cbranch_scc1 .Lv8a_3
	s_waitcnt vmcnt(8)

; #define PG8_WAIT_V(n) asm volatile("s_waitcnt vmcnt(" #n ")" ::: "memory")
; #define PG8_WAIT_L(n) asm volatile("s_waitcnt lgkmcnt(" #n ")" ::: "memory")
; #define PG8_BAR __builtin_amdgcn_s_barrier()
; #define PG8_SCHED __builtin_amdgcn_sched_barrier(0)
; template <class Epi>
; __device__ __forceinline__ void gemm_phase(LAS unsigned char* lds, const Gemm g, const StaticOrder& S, const Epi& E) {
;     ...
;         for (int t = 0; t < nt; t += 2) {
;     ...
;             PG8_WAIT_V(8); PG8_WAIT_L(0); PG8_BAR; PG8_MMA2B(1, At, At2, B0); PG8_BAR; PG8_SCHED;
;     ...
;         if (wr == 0) PG8_BAR;
.Lv8b_3:
	s_barrier
	s_add_i32 s62, s62, 2
	s_add_u32 s60, s60, 0x100
	s_addc_u32 s61, s61, 0
	s_cmp_gt_u32 s62, 13
	s_mov_b64 s[4:5], s[8:9]
	s_cbranch_scc0 .LBB0_233
	s_and_b64 vcc, exec, s[2:3]
	s_cbranch_vccz .LBB0_236
	s_barrier

; #define PG8_STAGE(bufoff, gbase, voff) do { _Pragma("unroll") for (int _i = 0; _i < 2; ++_i) { \
;         const unsigned _m0 = ldsu + (unsigned)(bufoff) + ldsw + (unsigned)(_i * 8192); \
;         asm volatile("s_mov_b32 m0, %2\n\ts_nop 0\n\tglobal_load_lds_dwordx4 %0, %1" :: "v"((voff)[_i]), "s"((const char*)(gbase)), "s"(_m0) : "memory"); } } while (0)
; #define PG8_LDA(dst, b, h) do { _Pragma("unroll") for (int m = 0; m < 4; ++m) _Pragma("unroll") for (int k = 0; k < 2; ++k) dst[m][k] = *(const LAS bf16x8*)(lds + PG8_SA(b, h) + aoff + m * 2048 + k * 1024); } while (0)
; #define PG8_LDB(dst, b, h) do { _Pragma("unroll") for (int n = 0; n < 2; ++n) _Pragma("unroll") for (int k = 0; k < 2; ++k) dst[n][k] = *(const LAS bf16x8*)(lds + bbase[b][h] + n * 2048 + k * 1024); } while (0)
; #define PG8_WAIT_V(n) asm volatile("s_waitcnt vmcnt(" #n ")" ::: "memory")
; #define PG8_WAIT_L(n) asm volatile("s_waitcnt lgkmcnt(" #n ")" ::: "memory")
; #define PG8_BAR __builtin_amdgcn_s_barrier()
; #define PG8_SCHED __builtin_amdgcn_sched_barrier(0)
; template <class Epi>
; __device__ __forceinline__ void gemm_phase(LAS unsigned char* lds, const Gemm g, const StaticOrder& S, const Epi& E) {
;     ...
;             PG8_LDB(B0, 0, 0); PG8_SCHED; PG8_LDA(At, 0, 0); PG8_LDA(At2, 0, 1); PG8_STAGE(PG8_SB(1, 1), b1 + hstepB, voffB);
;             PG8_WAIT_V(8); PG8_WAIT_L(0); PG8_BAR; PG8_MMA2B(0, At, At2, B0); PG8_BAR; PG8_SCHED;
.LBB0_584:
	ds_read_b128 v[128:131], v155
	ds_read_b128 v[132:135], v155 offset:1024
	ds_read_b128 v[136:139], v155 offset:2048
	ds_read_b128 v[140:143], v155 offset:3072
	s_add_u32 s10, s8, 0x100
	s_addc_u32 s11, s9, 0
	s_cmp_eq_u32 s68, 12
	s_cselect_b32 s84, s67, s87
	s_cselect_b32 s85, s43, s88
	s_cselect_b32 s90, s86, s10
	s_cselect_b32 s91, s39, s11
	s_add_u32 s96, s84, 0x80
	s_addc_u32 s97, s85, 0
	ds_read_b128 v[144:147], v156
	ds_read_b128 v[178:181], v156 offset:1024
	ds_read_b128 v[182:185], v156 offset:2048
	ds_read_b128 v[186:189], v156 offset:3072
	ds_read_b128 v[190:193], v156 offset:4096
	ds_read_b128 v[194:197], v156 offset:5120
	ds_read_b128 v[198:201], v156 offset:6144
	ds_read_b128 v[202:205], v156 offset:7168
	ds_read_b128 v[214:217], v156 offset:16384
	ds_read_b128 v[218:221], v156 offset:17408
	ds_read_b128 v[222:225], v156 offset:18432
	ds_read_b128 v[226:229], v156 offset:19456
	ds_read_b128 v[230:233], v156 offset:20480
	ds_read_b128 v[234:237], v156 offset:21504
	ds_read_b128 v[238:241], v156 offset:22528
	ds_read_b128 v[242:245], v156 offset:23552
	s_add_u32 s8, s8, 0x40080
	s_addc_u32 s9, s9, 0
	s_mov_b32 m0, s61
	s_nop 0
	global_load_lds_dwordx4 v151, s[8:9]
	s_mov_b32 m0, s64
	s_nop 0
	global_load_lds_dwordx4 v153, s[8:9]
	s_cmp_lg_u64 s[4:5], 0
	s_cbranch_scc1 .Lv8a_4
	s_waitcnt vmcnt(8)
.Lv8a_4:
	s_waitcnt lgkmcnt(0)
	s_barrier
	s_waitcnt lgkmcnt(14)
	v_mfma_f32_16x16x32_bf16 v[76:79], v[128:131], v[144:147], v[76:79]
	v_mfma_f32_16x16x32_bf16 v[72:75], v[136:139], v[144:147], v[72:75]
	s_waitcnt lgkmcnt(13)
	v_mfma_f32_16x16x32_bf16 v[64:67], v[128:131], v[182:185], v[64:67]
	v_mfma_f32_16x16x32_bf16 v[60:63], v[136:139], v[182:185], v[60:63]
	s_waitcnt lgkmcnt(11)
	v_mfma_f32_16x16x32_bf16 v[56:59], v[128:131], v[190:193], v[56:59]
	v_mfma_f32_16x16x32_bf16 v[52:55], v[136:139], v[190:193], v[52:55]
	s_waitcnt lgkmcnt(9)
	v_mfma_f32_16x16x32_bf16 v[112:115], v[128:131], v[198:201], v[112:115]
	v_mfma_f32_16x16x32_bf16 v[104:107], v[136:139], v[198:201], v[104:107]
	s_waitcnt lgkmcnt(7)
	v_mfma_f32_16x16x32_bf16 v[36:39], v[128:131], v[214:217], v[36:39]
	v_mfma_f32_16x16x32_bf16 v[32:35], v[136:139], v[214:217], v[32:35]
	s_waitcnt lgkmcnt(5)
	v_mfma_f32_16x16x32_bf16 v[28:31], v[128:131], v[222:225], v[28:31]
	v_mfma_f32_16x16x32_bf16 v[24:27], v[136:139], v[222:225], v[24:27]
	s_waitcnt lgkmcnt(3)
	v_mfma_f32_16x16x32_bf16 v[16:19], v[128:131], v[230:233], v[16:19]
	v_mfma_f32_16x16x32_bf16 v[12:15], v[136:139], v[230:233], v[12:15]
	s_waitcnt lgkmcnt(1)
	v_mfma_f32_16x16x32_bf16 v[88:91], v[128:131], v[238:241], v[88:91]
	v_mfma_f32_16x16x32_bf16 v[84:87], v[136:139], v[238:241], v[84:87]
	v_mfma_f32_16x16x32_bf16 v[76:79], v[132:135], v[178:181], v[76:79]
	v_mfma_f32_16x16x32_bf16 v[72:75], v[140:143], v[178:181], v[72:75]
	v_mfma_f32_16x16x32_bf16 v[64:67], v[132:135], v[186:189], v[64:67]
	v_mfma_f32_16x16x32_bf16 v[60:63], v[140:143], v[186:189], v[60:63]
	v_mfma_f32_16x16x32_bf16 v[56:59], v[132:135], v[194:197], v[56:59]
	v_mfma_f32_16x16x32_bf16 v[52:55], v[140:143], v[194:197], v[52:55]
	v_mfma_f32_16x16x32_bf16 v[112:115], v[132:135], v[202:205], v[112:115]
	v_mfma_f32_16x16x32_bf16 v[104:107], v[140:143], v[202:205], v[104:107]
	v_mfma_f32_16x16x32_bf16 v[36:39], v[132:135], v[218:221], v[36:39]
	v_mfma_f32_16x16x32_bf16 v[32:35], v[140:143], v[218:221], v[32:35]
	v_mfma_f32_16x16x32_bf16 v[28:31], v[132:135], v[226:229], v[28:31]
	v_mfma_f32_16x16x32_bf16 v[24:27], v[140:143], v[226:229], v[24:27]
	v_mfma_f32_16x16x32_bf16 v[16:19], v[132:135], v[234:237], v[16:19]
	v_mfma_f32_16x16x32_bf16 v[12:15], v[140:143], v[234:237], v[12:15]
	s_waitcnt lgkmcnt(0)
	v_mfma_f32_16x16x32_bf16 v[88:91], v[132:135], v[242:245], v[88:91]
	v_mfma_f32_16x16x32_bf16 v[84:87], v[140:143], v[242:245], v[84:87]
	s_cmp_eq_u64 s[4:5], 0
	s_cbranch_scc1 .Lv8b_4
	s_waitcnt vmcnt(8)
; #define PG8_STAGE(bufoff, gbase, voff) do { _Pragma("unroll") for (int _i = 0; _i < 2; ++_i) { \
;         const unsigned _m0 = ldsu + (unsigned)(bufoff) + ldsw + (unsigned)(_i * 8192); \
;         asm volatile("s_mov_b32 m0, %2\n\ts_nop 0\n\tglobal_load_lds_dwordx4 %0, %1" :: "v"((voff)[_i]), "s"((const char*)(gbase)), "s"(_m0) : "memory"); } } while (0)
; #define PG8_LDA(dst, b, h) do { _Pragma("unroll") for (int m = 0; m < 4; ++m) _Pragma("unroll") for (int k = 0; k < 2; ++k) dst[m][k] = *(const LAS bf16x8*)(lds + PG8_SA(b, h) + aoff + m * 2048 + k * 1024); } while (0)
; #define PG8_LDB(dst, b, h) do { _Pragma("unroll") for (int n = 0; n < 2; ++n) _Pragma("unroll") for (int k = 0; k < 2; ++k) dst[n][k] = *(const LAS bf16x8*)(lds + bbase[b][h] + n * 2048 + k * 1024); } while (0)
; #define PG8_WAIT_V(n) asm volatile("s_waitcnt vmcnt(" #n ")" ::: "memory")
; #define PG8_WAIT_L(n) asm volatile("s_waitcnt lgkmcnt(" #n ")" ::: "memory")
; #define PG8_BAR __builtin_amdgcn_s_barrier()
; #define PG8_SCHED __builtin_amdgcn_sched_barrier(0)
; template <class Epi>
; __device__ __forceinline__ void gemm_phase(LAS unsigned char* lds, const Gemm g, const StaticOrder& S, const Epi& E) {
;     ...
;             PG8_LDB(B0, 0, 0); PG8_SCHED; PG8_LDA(At, 0, 0); PG8_LDA(At2, 0, 1); PG8_STAGE(PG8_SB(1, 1), b1 + hstepB, voffB);
;             PG8_WAIT_V(8); PG8_WAIT_L(0); PG8_BAR; PG8_MMA2B(0, At, At2, B0); PG8_BAR; PG8_SCHED;
;             PG8_LDB(B0, 0, 1); PG8_STAGE(PG8_SB(0, 0), b2, voffB); PG8_STAGE(PG8_SA(0, 0), a2, voffA); PG8_STAGE(PG8_SA(0, 1), a2 + hstepA, voffA);
;             PG8_WAIT_V(8); PG8_WAIT_L(0); PG8_BAR; PG8_MMA2B(1, At, At2, B0); PG8_BAR; PG8_SCHED;
;             PG8_LDB(B0, 1, 0); PG8_SCHED; PG8_LDA(At, 1, 0); PG8_LDA(At2, 1, 1); PG8_STAGE(PG8_SB(0, 1), b2 + hstepB, voffB);
;             PG8_WAIT_V(8); PG8_WAIT_L(0); PG8_BAR; PG8_MMA2B(0, At, At2, B0); PG8_BAR; PG8_SCHED;
;             PG8_LDB(B0, 1, 1); PG8_STAGE(PG8_SB(1, 0), b3, voffB); PG8_STAGE(PG8_SA(1, 0), a3, voffA); PG8_STAGE(PG8_SA(1, 1), a3 + hstepA, voffA);
.Lv8b_4:
	s_barrier
	ds_read_b128 v[128:131], v157
	ds_read_b128 v[132:135], v157 offset:1024
	ds_read_b128 v[136:139], v157 offset:2048
	ds_read_b128 v[140:143], v157 offset:3072
	s_mov_b32 m0, s47
	s_nop 0
	global_load_lds_dwordx4 v151, s[90:91]
	s_mov_b32 m0, s48
	s_nop 0
	global_load_lds_dwordx4 v153, s[90:91]
	s_mov_b32 m0, s37
	s_nop 0
	global_load_lds_dwordx4 v150, s[84:85]
	s_mov_b32 m0, s49
	s_nop 0
	global_load_lds_dwordx4 v152, s[84:85]
	s_add_u32 s8, s84, 0x40000
	s_addc_u32 s9, s85, 0
	s_mov_b32 m0, s50
	s_nop 0
	global_load_lds_dwordx4 v150, s[8:9]
	s_mov_b32 m0, s51
	s_nop 0
	global_load_lds_dwordx4 v152, s[8:9]
	s_cmp_lg_u64 s[4:5], 0
	s_cbranch_scc1 .Lv8a_5
	s_waitcnt vmcnt(8)
.Lv8a_5:
	s_waitcnt lgkmcnt(0)
	s_barrier
	s_waitcnt lgkmcnt(3)
	v_mfma_f32_16x16x32_bf16 v[68:71], v[128:131], v[144:147], v[68:71]
	s_waitcnt lgkmcnt(1)
	v_mfma_f32_16x16x32_bf16 v[124:127], v[136:139], v[144:147], v[124:127]
	v_mfma_f32_16x16x32_bf16 v[48:51], v[128:131], v[182:185], v[48:51]
	v_mfma_f32_16x16x32_bf16 v[120:123], v[136:139], v[182:185], v[120:123]
	v_mfma_f32_16x16x32_bf16 v[44:47], v[128:131], v[190:193], v[44:47]
	v_mfma_f32_16x16x32_bf16 v[116:119], v[136:139], v[190:193], v[116:119]
	v_mfma_f32_16x16x32_bf16 v[40:43], v[128:131], v[198:201], v[40:43]
	v_mfma_f32_16x16x32_bf16 v[108:111], v[136:139], v[198:201], v[108:111]
	v_mfma_f32_16x16x32_bf16 v[20:23], v[128:131], v[214:217], v[20:23]
	v_mfma_f32_16x16x32_bf16 v[100:103], v[136:139], v[214:217], v[100:103]
	v_mfma_f32_16x16x32_bf16 v[8:11], v[128:131], v[222:225], v[8:11]
	v_mfma_f32_16x16x32_bf16 v[96:99], v[136:139], v[222:225], v[96:99]
	v_mfma_f32_16x16x32_bf16 v[4:7], v[128:131], v[230:233], v[4:7]
	v_mfma_f32_16x16x32_bf16 v[92:95], v[136:139], v[230:233], v[92:95]
	v_mfma_f32_16x16x32_bf16 v[0:3], v[128:131], v[238:241], v[0:3]
	v_mfma_f32_16x16x32_bf16 v[80:83], v[136:139], v[238:241], v[80:83]
	v_mfma_f32_16x16x32_bf16 v[68:71], v[132:135], v[178:181], v[68:71]
	s_waitcnt lgkmcnt(0)
	v_mfma_f32_16x16x32_bf16 v[124:127], v[140:143], v[178:181], v[124:127]
	v_mfma_f32_16x16x32_bf16 v[48:51], v[132:135], v[186:189], v[48:51]
	v_mfma_f32_16x16x32_bf16 v[120:123], v[140:143], v[186:189], v[120:123]
	v_mfma_f32_16x16x32_bf16 v[44:47], v[132:135], v[194:197], v[44:47]
	v_mfma_f32_16x16x32_bf16 v[116:119], v[140:143], v[194:197], v[116:119]
	v_mfma_f32_16x16x32_bf16 v[40:43], v[132:135], v[202:205], v[40:43]
	v_mfma_f32_16x16x32_bf16 v[108:111], v[140:143], v[202:205], v[108:111]
	v_mfma_f32_16x16x32_bf16 v[20:23], v[132:135], v[218:221], v[20:23]
	v_mfma_f32_16x16x32_bf16 v[100:103], v[140:143], v[218:221], v[100:103]
	v_mfma_f32_16x16x32_bf16 v[8:11], v[132:135], v[226:229], v[8:11]
	v_mfma_f32_16x16x32_bf16 v[96:99], v[140:143], v[226:229], v[96:99]
	v_mfma_f32_16x16x32_bf16 v[4:7], v[132:135], v[234:237], v[4:7]
	v_mfma_f32_16x16x32_bf16 v[92:95], v[140:143], v[234:237], v[92:95]
	v_mfma_f32_16x16x32_bf16 v[0:3], v[132:135], v[242:245], v[0:3]
	v_mfma_f32_16x16x32_bf16 v[80:83], v[140:143], v[242:245], v[80:83]
	s_cmp_eq_u64 s[4:5], 0
	s_cbranch_scc1 .Lv8b_5
	s_waitcnt vmcnt(8)
.Lv8b_5:
	s_barrier
	ds_read_b128 v[128:131], v158
	ds_read_b128 v[132:135], v158 offset:1024
	ds_read_b128 v[136:139], v158 offset:2048
	ds_read_b128 v[140:143], v158 offset:3072
	ds_read_b128 v[144:147], v156 offset:32768
	ds_read_b128 v[178:181], v156 offset:33792
	ds_read_b128 v[182:185], v156 offset:34816
	ds_read_b128 v[186:189], v156 offset:35840
	ds_read_b128 v[190:193], v156 offset:36864
	ds_read_b128 v[194:197], v156 offset:37888
	ds_read_b128 v[198:201], v156 offset:38912
	ds_read_b128 v[202:205], v156 offset:39936
	ds_read_b128 v[214:217], v156 offset:49152
	ds_read_b128 v[218:221], v156 offset:50176
	ds_read_b128 v[222:225], v156 offset:51200
	ds_read_b128 v[226:229], v156 offset:52224
	ds_read_b128 v[230:233], v156 offset:53248
	ds_read_b128 v[234:237], v156 offset:54272
	ds_read_b128 v[238:241], v156 offset:55296
	ds_read_b128 v[242:245], v156 offset:56320
	s_add_u32 s8, s90, 0x40000
	s_addc_u32 s9, s91, 0
	s_mov_b32 m0, s52
	s_nop 0
	global_load_lds_dwordx4 v151, s[8:9]
	s_mov_b32 m0, s53
	s_nop 0
	global_load_lds_dwordx4 v153, s[8:9]
	s_cmp_lg_u64 s[4:5], 0
	s_cbranch_scc1 .Lv8a_6
	s_waitcnt vmcnt(8)

; #define PG8_STAGE(bufoff, gbase, voff) do { _Pragma("unroll") for (int _i = 0; _i < 2; ++_i) { \
;         const unsigned _m0 = ldsu + (unsigned)(bufoff) + ldsw + (unsigned)(_i * 8192); \
;         asm volatile("s_mov_b32 m0, %2\n\ts_nop 0\n\tglobal_load_lds_dwordx4 %0, %1" :: "v"((voff)[_i]), "s"((const char*)(gbase)), "s"(_m0) : "memory"); } } while (0)
; #define PG8_LDB(dst, b, h) do { _Pragma("unroll") for (int n = 0; n < 2; ++n) _Pragma("unroll") for (int k = 0; k < 2; ++k) dst[n][k] = *(const LAS bf16x8*)(lds + bbase[b][h] + n * 2048 + k * 1024); } while (0)
; #define PG8_WAIT_V(n) asm volatile("s_waitcnt vmcnt(" #n ")" ::: "memory")
; #define PG8_WAIT_L(n) asm volatile("s_waitcnt lgkmcnt(" #n ")" ::: "memory")
; #define PG8_BAR __builtin_amdgcn_s_barrier()
; #define PG8_SCHED __builtin_amdgcn_sched_barrier(0)
; template <class Epi>
; __device__ __forceinline__ void gemm_phase(LAS unsigned char* lds, const Gemm g, const StaticOrder& S, const Epi& E) {
;     ...
;             PG8_LDB(B0, 1, 1); PG8_STAGE(PG8_SB(1, 0), b3, voffB); PG8_STAGE(PG8_SA(1, 0), a3, voffA); PG8_STAGE(PG8_SA(1, 1), a3 + hstepA, voffA);
;             PG8_WAIT_V(8); PG8_WAIT_L(0); PG8_BAR; PG8_MMA2B(1, At, At2, B0); PG8_BAR; PG8_SCHED;
.Lv8b_6:
	s_barrier
	s_add_u32 s8, s90, 0x80
	ds_read_b128 v[128:131], v159
	ds_read_b128 v[132:135], v159 offset:1024
	ds_read_b128 v[136:139], v159 offset:2048
	ds_read_b128 v[140:143], v159 offset:3072
	s_addc_u32 s9, s91, 0
	s_mov_b32 m0, s55
	s_nop 0
	global_load_lds_dwordx4 v151, s[8:9]
	s_mov_b32 m0, s56
	s_nop 0
	global_load_lds_dwordx4 v153, s[8:9]
	s_mov_b32 m0, s57
	s_nop 0
	global_load_lds_dwordx4 v150, s[96:97]
	s_mov_b32 m0, s58
	s_nop 0
	global_load_lds_dwordx4 v152, s[96:97]
	s_add_u32 s8, s84, 0x40080
	s_addc_u32 s9, s85, 0
	s_mov_b32 m0, s59
	s_nop 0
	global_load_lds_dwordx4 v150, s[8:9]
	s_mov_b32 m0, s60
	s_nop 0
	global_load_lds_dwordx4 v152, s[8:9]
	s_cmp_lg_u64 s[4:5], 0
	s_cbranch_scc1 .Lv8a_7
	s_waitcnt vmcnt(8)

; #define PG8_STAGE(bufoff, gbase, voff) do { _Pragma("unroll") for (int _i = 0; _i < 2; ++_i) { \
;         const unsigned _m0 = ldsu + (unsigned)(bufoff) + ldsw + (unsigned)(_i * 8192); \
;         asm volatile("s_mov_b32 m0, %2\n\ts_nop 0\n\tglobal_load_lds_dwordx4 %0, %1" :: "v"((voff)[_i]), "s"((const char*)(gbase)), "s"(_m0) : "memory"); } } while (0)
; #define PG8_LDA(dst, b, h) do { _Pragma("unroll") for (int m = 0; m < 4; ++m) _Pragma("unroll") for (int k = 0; k < 2; ++k) dst[m][k] = *(const LAS bf16x8*)(lds + PG8_SA(b, h) + aoff + m * 2048 + k * 1024); } while (0)
; #define PG8_LDB(dst, b, h) do { _Pragma("unroll") for (int n = 0; n < 2; ++n) _Pragma("unroll") for (int k = 0; k < 2; ++k) dst[n][k] = *(const LAS bf16x8*)(lds + bbase[b][h] + n * 2048 + k * 1024); } while (0)
; #define PG8_WAIT_V(n) asm volatile("s_waitcnt vmcnt(" #n ")" ::: "memory")
; template <class Epi>
; __device__ __forceinline__ void gemm_phase(LAS unsigned char* lds, const Gemm g, const StaticOrder& S, const Epi& E) {
;     ...
;         for (int t = 0; t < nt; t += 2) {
;             const bool last = (t == nt - 2);
;             const char* a2 = last ? nA : cA + (size_t)(t + 2) * kstep; const char* b2 = last ? nB : cB + (size_t)(t + 2) * kstep;
;             const char* a3 = a2 + kstep; const char* b3 = b2 + kstep;
;             const char* b1 = cB + (size_t)(t + 1) * kstep;
;             PG8_LDB(B0, 0, 0); PG8_SCHED; PG8_LDA(At, 0, 0); PG8_LDA(At2, 0, 1); PG8_STAGE(PG8_SB(1, 1), b1 + hstepB, voffB);
;             PG8_WAIT_V(8); PG8_WAIT_L(0); PG8_BAR; PG8_MMA2B(0, At, At2, B0); PG8_BAR; PG8_SCHED;
;             PG8_LDB(B0, 0, 1); PG8_STAGE(PG8_SB(0, 0), b2, voffB); PG8_STAGE(PG8_SA(0, 0), a2, voffA); PG8_STAGE(PG8_SA(0, 1), a2 + hstepA, voffA);
;             PG8_WAIT_V(8); PG8_WAIT_L(0); PG8_BAR; PG8_MMA2B(1, At, At2, B0); PG8_BAR; PG8_SCHED;
;             PG8_LDB(B0, 1, 0); PG8_SCHED; PG8_LDA(At, 1, 0); PG8_LDA(At2, 1, 1); PG8_STAGE(PG8_SB(0, 1), b2 + hstepB, voffB);
;             PG8_WAIT_V(8); PG8_WAIT_L(0); PG8_BAR; PG8_MMA2B(0, At, At2, B0); PG8_BAR; PG8_SCHED;
;             PG8_LDB(B0, 1, 1); PG8_STAGE(PG8_SB(1, 0), b3, voffB); PG8_STAGE(PG8_SA(1, 0), a3, voffA); PG8_STAGE(PG8_SA(1, 1), a3 + hstepA, voffA);
;             PG8_WAIT_V(8); PG8_WAIT_L(0); PG8_BAR; PG8_MMA2B(1, At, At2, B0); PG8_BAR; PG8_SCHED;
;         }
;         if (wr == 0) PG8_BAR;
.Lv8b_7:
	s_barrier
	s_add_i32 s68, s68, 2
	s_add_u32 s87, s87, 0x100
	s_addc_u32 s88, s88, 0
	s_cmp_gt_u32 s68, 13
	s_mov_b64 s[8:9], s[10:11]
	s_cbranch_scc0 .LBB0_584
	s_and_b64 vcc, exec, s[4:5]
	s_cbranch_vccz .LBB0_587
	s_barrier

; #define PG8_STAGE(bufoff, gbase, voff) do { _Pragma("unroll") for (int _i = 0; _i < 2; ++_i) { \
;         const unsigned _m0 = ldsu + (unsigned)(bufoff) + ldsw + (unsigned)(_i * 8192); \
;         asm volatile("s_mov_b32 m0, %2\n\ts_nop 0\n\tglobal_load_lds_dwordx4 %0, %1" :: "v"((voff)[_i]), "s"((const char*)(gbase)), "s"(_m0) : "memory"); } } while (0)
; #define PG8_LDA(dst, b, h) do { _Pragma("unroll") for (int m = 0; m < 4; ++m) _Pragma("unroll") for (int k = 0; k < 2; ++k) dst[m][k] = *(const LAS bf16x8*)(lds + PG8_SA(b, h) + aoff + m * 2048 + k * 1024); } while (0)
; #define PG8_LDB(dst, b, h) do { _Pragma("unroll") for (int n = 0; n < 2; ++n) _Pragma("unroll") for (int k = 0; k < 2; ++k) dst[n][k] = *(const LAS bf16x8*)(lds + bbase[b][h] + n * 2048 + k * 1024); } while (0)
; #define PG8_WAIT_V(n) asm volatile("s_waitcnt vmcnt(" #n ")" ::: "memory")
; #define PG8_WAIT_L(n) asm volatile("s_waitcnt lgkmcnt(" #n ")" ::: "memory")
; #define PG8_BAR __builtin_amdgcn_s_barrier()
; #define PG8_SCHED __builtin_amdgcn_sched_barrier(0)
; template <class Epi>
; __device__ __forceinline__ void gemm_phase(LAS unsigned char* lds, const Gemm g, const StaticOrder& S, const Epi& E) {
;     ...
;             const bool last = (t == nt - 2);
;             const char* a2 = last ? nA : cA + (size_t)(t + 2) * kstep; const char* b2 = last ? nB : cB + (size_t)(t + 2) * kstep;
;             const char* a3 = a2 + kstep; const char* b3 = b2 + kstep;
;             const char* b1 = cB + (size_t)(t + 1) * kstep;
;             PG8_LDB(B0, 0, 0); PG8_SCHED; PG8_LDA(At, 0, 0); PG8_LDA(At2, 0, 1); PG8_STAGE(PG8_SB(1, 1), b1 + hstepB, voffB);
;             PG8_WAIT_V(8); PG8_WAIT_L(0); PG8_BAR; PG8_MMA2B(0, At, At2, B0); PG8_BAR; PG8_SCHED;
.LBB0_943:
	ds_read_b128 v[128:131], v138
	ds_read_b128 v[144:147], v138 offset:1024
	ds_read_b128 v[148:151], v138 offset:2048
	ds_read_b128 v[152:155], v138 offset:3072
	s_cmp_eq_u32 s68, 12
	s_cselect_b32 s38, s66, s84
	s_cselect_b32 s39, s13, s85
	s_cselect_b32 s82, s67, s86
	s_cselect_b32 s83, s5, s87
	s_add_u32 s42, s38, 0x80
	s_addc_u32 s43, s39, 0
	s_add_u32 s80, s82, 0x80
	s_addc_u32 s81, s83, 0
	ds_read_b128 v[156:159], v139
	ds_read_b128 v[166:169], v139 offset:1024
	ds_read_b128 v[178:181], v139 offset:2048
	ds_read_b128 v[182:185], v139 offset:3072
	ds_read_b128 v[186:189], v139 offset:4096
	ds_read_b128 v[190:193], v139 offset:5120
	ds_read_b128 v[194:197], v139 offset:6144
	ds_read_b128 v[198:201], v139 offset:7168
	ds_read_b128 v[202:205], v139 offset:16384
	ds_read_b128 v[214:217], v139 offset:17408
	ds_read_b128 v[218:221], v139 offset:18432
	ds_read_b128 v[222:225], v139 offset:19456
	ds_read_b128 v[226:229], v139 offset:20480
	ds_read_b128 v[230:233], v139 offset:21504
	ds_read_b128 v[234:237], v139 offset:22528
	ds_read_b128 v[238:241], v139 offset:23552
	s_mov_b32 m0, s61
	s_nop 0
	global_load_lds_dwordx4 v133, s[6:7]
	s_mov_b32 m0, s63
	s_nop 0
	global_load_lds_dwordx4 v135, s[6:7]
	s_cmp_lg_u64 s[2:3], 0
	s_cbranch_scc1 .Lv8a_8
	s_waitcnt vmcnt(8)
.Lv8a_8:
	s_waitcnt lgkmcnt(0)
	s_barrier
	s_waitcnt lgkmcnt(14)
	v_mfma_f32_16x16x32_bf16 v[124:127], v[128:131], v[156:159], v[124:127]
	v_mfma_f32_16x16x32_bf16 v[120:123], v[148:151], v[156:159], v[120:123]
	s_waitcnt lgkmcnt(13)
	v_mfma_f32_16x16x32_bf16 v[108:111], v[128:131], v[178:181], v[108:111]
	v_mfma_f32_16x16x32_bf16 v[104:107], v[148:151], v[178:181], v[104:107]
	s_waitcnt lgkmcnt(11)
	v_mfma_f32_16x16x32_bf16 v[92:95], v[128:131], v[186:189], v[92:95]
	v_mfma_f32_16x16x32_bf16 v[88:91], v[148:151], v[186:189], v[88:91]
	s_waitcnt lgkmcnt(9)
	v_mfma_f32_16x16x32_bf16 v[76:79], v[128:131], v[194:197], v[76:79]
	v_mfma_f32_16x16x32_bf16 v[72:75], v[148:151], v[194:197], v[72:75]
	s_waitcnt lgkmcnt(7)
	v_mfma_f32_16x16x32_bf16 v[60:63], v[128:131], v[202:205], v[60:63]
	v_mfma_f32_16x16x32_bf16 v[56:59], v[148:151], v[202:205], v[56:59]
	s_waitcnt lgkmcnt(5)
	v_mfma_f32_16x16x32_bf16 v[44:47], v[128:131], v[218:221], v[44:47]
	v_mfma_f32_16x16x32_bf16 v[40:43], v[148:151], v[218:221], v[40:43]
	s_waitcnt lgkmcnt(3)
	v_mfma_f32_16x16x32_bf16 v[28:31], v[128:131], v[226:229], v[28:31]
	v_mfma_f32_16x16x32_bf16 v[24:27], v[148:151], v[226:229], v[24:27]
	s_waitcnt lgkmcnt(1)
	v_mfma_f32_16x16x32_bf16 v[12:15], v[128:131], v[234:237], v[12:15]
	v_mfma_f32_16x16x32_bf16 v[8:11], v[148:151], v[234:237], v[8:11]
	v_mfma_f32_16x16x32_bf16 v[124:127], v[144:147], v[166:169], v[124:127]
	v_mfma_f32_16x16x32_bf16 v[120:123], v[152:155], v[166:169], v[120:123]
	v_mfma_f32_16x16x32_bf16 v[108:111], v[144:147], v[182:185], v[108:111]
	v_mfma_f32_16x16x32_bf16 v[104:107], v[152:155], v[182:185], v[104:107]
	v_mfma_f32_16x16x32_bf16 v[92:95], v[144:147], v[190:193], v[92:95]
	v_mfma_f32_16x16x32_bf16 v[88:91], v[152:155], v[190:193], v[88:91]
	v_mfma_f32_16x16x32_bf16 v[76:79], v[144:147], v[198:201], v[76:79]
	v_mfma_f32_16x16x32_bf16 v[72:75], v[152:155], v[198:201], v[72:75]
	v_mfma_f32_16x16x32_bf16 v[60:63], v[144:147], v[214:217], v[60:63]
	v_mfma_f32_16x16x32_bf16 v[56:59], v[152:155], v[214:217], v[56:59]
	v_mfma_f32_16x16x32_bf16 v[44:47], v[144:147], v[222:225], v[44:47]
	v_mfma_f32_16x16x32_bf16 v[40:43], v[152:155], v[222:225], v[40:43]
	v_mfma_f32_16x16x32_bf16 v[28:31], v[144:147], v[230:233], v[28:31]
	v_mfma_f32_16x16x32_bf16 v[24:27], v[152:155], v[230:233], v[24:27]
	s_waitcnt lgkmcnt(0)
	v_mfma_f32_16x16x32_bf16 v[12:15], v[144:147], v[238:241], v[12:15]
	v_mfma_f32_16x16x32_bf16 v[8:11], v[152:155], v[238:241], v[8:11]
	s_cmp_eq_u64 s[2:3], 0
	s_cbranch_scc1 .Lv8b_8
	s_waitcnt vmcnt(8)
; #define PG8_STAGE(bufoff, gbase, voff) do { _Pragma("unroll") for (int _i = 0; _i < 2; ++_i) { \
;         const unsigned _m0 = ldsu + (unsigned)(bufoff) + ldsw + (unsigned)(_i * 8192); \
;         asm volatile("s_mov_b32 m0, %2\n\ts_nop 0\n\tglobal_load_lds_dwordx4 %0, %1" :: "v"((voff)[_i]), "s"((const char*)(gbase)), "s"(_m0) : "memory"); } } while (0)
; #define PG8_LDA(dst, b, h) do { _Pragma("unroll") for (int m = 0; m < 4; ++m) _Pragma("unroll") for (int k = 0; k < 2; ++k) dst[m][k] = *(const LAS bf16x8*)(lds + PG8_SA(b, h) + aoff + m * 2048 + k * 1024); } while (0)
; #define PG8_LDB(dst, b, h) do { _Pragma("unroll") for (int n = 0; n < 2; ++n) _Pragma("unroll") for (int k = 0; k < 2; ++k) dst[n][k] = *(const LAS bf16x8*)(lds + bbase[b][h] + n * 2048 + k * 1024); } while (0)
; #define PG8_WAIT_V(n) asm volatile("s_waitcnt vmcnt(" #n ")" ::: "memory")
; #define PG8_WAIT_L(n) asm volatile("s_waitcnt lgkmcnt(" #n ")" ::: "memory")
; #define PG8_BAR __builtin_amdgcn_s_barrier()
; #define PG8_SCHED __builtin_amdgcn_sched_barrier(0)
; template <class Epi>
; __device__ __forceinline__ void gemm_phase(LAS unsigned char* lds, const Gemm g, const StaticOrder& S, const Epi& E) {
;     ...
;             PG8_LDB(B0, 0, 1); PG8_STAGE(PG8_SB(0, 0), b2, voffB); PG8_STAGE(PG8_SA(0, 0), a2, voffA); PG8_STAGE(PG8_SA(0, 1), a2 + hstepA, voffA);
;             PG8_WAIT_V(8); PG8_WAIT_L(0); PG8_BAR; PG8_MMA2B(1, At, At2, B0); PG8_BAR; PG8_SCHED;
;             PG8_LDB(B0, 1, 0); PG8_SCHED; PG8_LDA(At, 1, 0); PG8_LDA(At2, 1, 1); PG8_STAGE(PG8_SB(0, 1), b2 + hstepB, voffB);
.Lv8b_8:
	s_barrier
	ds_read_b128 v[128:131], v140
	ds_read_b128 v[144:147], v140 offset:1024
	ds_read_b128 v[148:151], v140 offset:2048
	ds_read_b128 v[152:155], v140 offset:3072
	s_mov_b32 m0, s48
	s_nop 0
	global_load_lds_dwordx4 v133, s[82:83]
	s_mov_b32 m0, s49
	s_nop 0
	global_load_lds_dwordx4 v135, s[82:83]
	s_mov_b32 m0, s47
	s_nop 0
	global_load_lds_dwordx4 v132, s[38:39]
	s_mov_b32 m0, s50
	s_nop 0
	global_load_lds_dwordx4 v134, s[38:39]
	s_add_u32 s88, s38, 0x40000
	s_addc_u32 s89, s39, 0
	s_mov_b32 m0, s51
	s_nop 0
	global_load_lds_dwordx4 v132, s[88:89]
	s_mov_b32 m0, s52
	s_nop 0
	global_load_lds_dwordx4 v134, s[88:89]
	s_cmp_lg_u64 s[2:3], 0
	s_cbranch_scc1 .Lv8a_9
	s_waitcnt vmcnt(8)
.Lv8a_9:
	s_waitcnt lgkmcnt(0)
	s_barrier
	s_waitcnt lgkmcnt(3)
	v_mfma_f32_16x16x32_bf16 v[116:119], v[128:131], v[156:159], v[116:119]
	s_waitcnt lgkmcnt(1)
	v_mfma_f32_16x16x32_bf16 v[112:115], v[148:151], v[156:159], v[112:115]
	v_mfma_f32_16x16x32_bf16 v[100:103], v[128:131], v[178:181], v[100:103]
	v_mfma_f32_16x16x32_bf16 v[96:99], v[148:151], v[178:181], v[96:99]
	v_mfma_f32_16x16x32_bf16 v[84:87], v[128:131], v[186:189], v[84:87]
	v_mfma_f32_16x16x32_bf16 v[80:83], v[148:151], v[186:189], v[80:83]
	v_mfma_f32_16x16x32_bf16 v[68:71], v[128:131], v[194:197], v[68:71]
	v_mfma_f32_16x16x32_bf16 v[64:67], v[148:151], v[194:197], v[64:67]
	v_mfma_f32_16x16x32_bf16 v[52:55], v[128:131], v[202:205], v[52:55]
	v_mfma_f32_16x16x32_bf16 v[48:51], v[148:151], v[202:205], v[48:51]
	v_mfma_f32_16x16x32_bf16 v[36:39], v[128:131], v[218:221], v[36:39]
	v_mfma_f32_16x16x32_bf16 v[32:35], v[148:151], v[218:221], v[32:35]
	v_mfma_f32_16x16x32_bf16 v[20:23], v[128:131], v[226:229], v[20:23]
	v_mfma_f32_16x16x32_bf16 v[16:19], v[148:151], v[226:229], v[16:19]
	v_mfma_f32_16x16x32_bf16 v[4:7], v[128:131], v[234:237], v[4:7]
	v_mfma_f32_16x16x32_bf16 v[0:3], v[148:151], v[234:237], v[0:3]
	v_mfma_f32_16x16x32_bf16 v[116:119], v[144:147], v[166:169], v[116:119]
	s_waitcnt lgkmcnt(0)
	v_mfma_f32_16x16x32_bf16 v[112:115], v[152:155], v[166:169], v[112:115]
	v_mfma_f32_16x16x32_bf16 v[100:103], v[144:147], v[182:185], v[100:103]
	v_mfma_f32_16x16x32_bf16 v[96:99], v[152:155], v[182:185], v[96:99]
	v_mfma_f32_16x16x32_bf16 v[84:87], v[144:147], v[190:193], v[84:87]
	v_mfma_f32_16x16x32_bf16 v[80:83], v[152:155], v[190:193], v[80:83]
	v_mfma_f32_16x16x32_bf16 v[68:71], v[144:147], v[198:201], v[68:71]
	v_mfma_f32_16x16x32_bf16 v[64:67], v[152:155], v[198:201], v[64:67]
	v_mfma_f32_16x16x32_bf16 v[52:55], v[144:147], v[214:217], v[52:55]
	v_mfma_f32_16x16x32_bf16 v[48:51], v[152:155], v[214:217], v[48:51]
	v_mfma_f32_16x16x32_bf16 v[36:39], v[144:147], v[222:225], v[36:39]
	v_mfma_f32_16x16x32_bf16 v[32:35], v[152:155], v[222:225], v[32:35]
	v_mfma_f32_16x16x32_bf16 v[20:23], v[144:147], v[230:233], v[20:23]
	v_mfma_f32_16x16x32_bf16 v[16:19], v[152:155], v[230:233], v[16:19]
	v_mfma_f32_16x16x32_bf16 v[4:7], v[144:147], v[238:241], v[4:7]
	v_mfma_f32_16x16x32_bf16 v[0:3], v[152:155], v[238:241], v[0:3]
	s_cmp_eq_u64 s[2:3], 0
	s_cbranch_scc1 .Lv8b_9
	s_waitcnt vmcnt(8)
.Lv8b_9:
	s_barrier
	ds_read_b128 v[128:131], v141
	ds_read_b128 v[144:147], v141 offset:1024
	ds_read_b128 v[148:151], v141 offset:2048
	ds_read_b128 v[152:155], v141 offset:3072
	ds_read_b128 v[156:159], v139 offset:32768
	ds_read_b128 v[166:169], v139 offset:33792
	ds_read_b128 v[178:181], v139 offset:34816
	ds_read_b128 v[182:185], v139 offset:35840
	ds_read_b128 v[186:189], v139 offset:36864
	ds_read_b128 v[190:193], v139 offset:37888
	ds_read_b128 v[194:197], v139 offset:38912
	ds_read_b128 v[198:201], v139 offset:39936
	ds_read_b128 v[202:205], v139 offset:49152
	ds_read_b128 v[214:217], v139 offset:50176
	ds_read_b128 v[218:221], v139 offset:51200
	ds_read_b128 v[222:225], v139 offset:52224
	ds_read_b128 v[226:229], v139 offset:53248
	ds_read_b128 v[230:233], v139 offset:54272
	ds_read_b128 v[234:237], v139 offset:55296
	ds_read_b128 v[238:241], v139 offset:56320
	s_add_u32 s82, s82, 0x40000
	s_addc_u32 s83, s83, 0
	s_mov_b32 m0, s53
	s_nop 0
	global_load_lds_dwordx4 v133, s[82:83]
	s_mov_b32 m0, s54
	s_nop 0
	global_load_lds_dwordx4 v135, s[82:83]
	s_cmp_lg_u64 s[2:3], 0
	s_cbranch_scc1 .Lv8a_10
	s_waitcnt vmcnt(8)

; #define PG8_STAGE(bufoff, gbase, voff) do { _Pragma("unroll") for (int _i = 0; _i < 2; ++_i) { \
;         const unsigned _m0 = ldsu + (unsigned)(bufoff) + ldsw + (unsigned)(_i * 8192); \
;         asm volatile("s_mov_b32 m0, %2\n\ts_nop 0\n\tglobal_load_lds_dwordx4 %0, %1" :: "v"((voff)[_i]), "s"((const char*)(gbase)), "s"(_m0) : "memory"); } } while (0)
; #define PG8_LDB(dst, b, h) do { _Pragma("unroll") for (int n = 0; n < 2; ++n) _Pragma("unroll") for (int k = 0; k < 2; ++k) dst[n][k] = *(const LAS bf16x8*)(lds + bbase[b][h] + n * 2048 + k * 1024); } while (0)
; #define PG8_WAIT_V(n) asm volatile("s_waitcnt vmcnt(" #n ")" ::: "memory")
; #define PG8_WAIT_L(n) asm volatile("s_waitcnt lgkmcnt(" #n ")" ::: "memory")
; #define PG8_BAR __builtin_amdgcn_s_barrier()
; #define PG8_SCHED __builtin_amdgcn_sched_barrier(0)
; template <class Epi>
; __device__ __forceinline__ void gemm_phase(LAS unsigned char* lds, const Gemm g, const StaticOrder& S, const Epi& E) {
;     ...
;             PG8_LDB(B0, 1, 1); PG8_STAGE(PG8_SB(1, 0), b3, voffB); PG8_STAGE(PG8_SA(1, 0), a3, voffA); PG8_STAGE(PG8_SA(1, 1), a3 + hstepA, voffA);
;             PG8_WAIT_V(8); PG8_WAIT_L(0); PG8_BAR; PG8_MMA2B(1, At, At2, B0); PG8_BAR; PG8_SCHED;
.Lv8b_10:
	s_barrier
	ds_read_b128 v[128:131], v142
	ds_read_b128 v[144:147], v142 offset:1024
	ds_read_b128 v[148:151], v142 offset:2048
	ds_read_b128 v[152:155], v142 offset:3072
	s_mov_b32 m0, s55
	s_nop 0
	global_load_lds_dwordx4 v133, s[80:81]
	s_mov_b32 m0, s56
	s_nop 0
	global_load_lds_dwordx4 v135, s[80:81]
	s_mov_b32 m0, s57
	s_nop 0
	global_load_lds_dwordx4 v132, s[42:43]
	s_mov_b32 m0, s58
	s_nop 0
	global_load_lds_dwordx4 v134, s[42:43]
	s_add_u32 s38, s38, 0x40080
	s_addc_u32 s39, s39, 0
	s_mov_b32 m0, s59
	s_nop 0
	global_load_lds_dwordx4 v132, s[38:39]
	s_mov_b32 m0, s60
	s_nop 0
	global_load_lds_dwordx4 v134, s[38:39]
	s_cmp_lg_u64 s[2:3], 0
	s_cbranch_scc1 .Lv8a_11
	s_waitcnt vmcnt(8)

; #define PG8_STAGE(bufoff, gbase, voff) do { _Pragma("unroll") for (int _i = 0; _i < 2; ++_i) { \
;         const unsigned _m0 = ldsu + (unsigned)(bufoff) + ldsw + (unsigned)(_i * 8192); \
;         asm volatile("s_mov_b32 m0, %2\n\ts_nop 0\n\tglobal_load_lds_dwordx4 %0, %1" :: "v"((voff)[_i]), "s"((const char*)(gbase)), "s"(_m0) : "memory"); } } while (0)
; #define PG8_LDA(dst, b, h) do { _Pragma("unroll") for (int m = 0; m < 4; ++m) _Pragma("unroll") for (int k = 0; k < 2; ++k) dst[m][k] = *(const LAS bf16x8*)(lds + PG8_SA(b, h) + aoff + m * 2048 + k * 1024); } while (0)
; #define PG8_LDB(dst, b, h) do { _Pragma("unroll") for (int n = 0; n < 2; ++n) _Pragma("unroll") for (int k = 0; k < 2; ++k) dst[n][k] = *(const LAS bf16x8*)(lds + bbase[b][h] + n * 2048 + k * 1024); } while (0)
; #define PG8_WAIT_V(n) asm volatile("s_waitcnt vmcnt(" #n ")" ::: "memory")
; template <class Epi>
; __device__ __forceinline__ void gemm_phase(LAS unsigned char* lds, const Gemm g, const StaticOrder& S, const Epi& E) {
;     ...
;         for (int t = 0; t < nt; t += 2) {
;             const bool last = (t == nt - 2);
;             const char* a2 = last ? nA : cA + (size_t)(t + 2) * kstep; const char* b2 = last ? nB : cB + (size_t)(t + 2) * kstep;
;             const char* a3 = a2 + kstep; const char* b3 = b2 + kstep;
;             const char* b1 = cB + (size_t)(t + 1) * kstep;
;             PG8_LDB(B0, 0, 0); PG8_SCHED; PG8_LDA(At, 0, 0); PG8_LDA(At2, 0, 1); PG8_STAGE(PG8_SB(1, 1), b1 + hstepB, voffB);
;             PG8_WAIT_V(8); PG8_WAIT_L(0); PG8_BAR; PG8_MMA2B(0, At, At2, B0); PG8_BAR; PG8_SCHED;
;             PG8_LDB(B0, 0, 1); PG8_STAGE(PG8_SB(0, 0), b2, voffB); PG8_STAGE(PG8_SA(0, 0), a2, voffA); PG8_STAGE(PG8_SA(0, 1), a2 + hstepA, voffA);
;             PG8_WAIT_V(8); PG8_WAIT_L(0); PG8_BAR; PG8_MMA2B(1, At, At2, B0); PG8_BAR; PG8_SCHED;
;             PG8_LDB(B0, 1, 0); PG8_SCHED; PG8_LDA(At, 1, 0); PG8_LDA(At2, 1, 1); PG8_STAGE(PG8_SB(0, 1), b2 + hstepB, voffB);
;             PG8_WAIT_V(8); PG8_WAIT_L(0); PG8_BAR; PG8_MMA2B(0, At, At2, B0); PG8_BAR; PG8_SCHED;
;             PG8_LDB(B0, 1, 1); PG8_STAGE(PG8_SB(1, 0), b3, voffB); PG8_STAGE(PG8_SA(1, 0), a3, voffA); PG8_STAGE(PG8_SA(1, 1), a3 + hstepA, voffA);
;             PG8_WAIT_V(8); PG8_WAIT_L(0); PG8_BAR; PG8_MMA2B(1, At, At2, B0); PG8_BAR; PG8_SCHED;
;         }
;         if (wr == 0) PG8_BAR;
.Lv8b_11:
	s_barrier
	s_add_i32 s68, s68, 2
	s_add_u32 s6, s6, 0x100
	s_addc_u32 s7, s7, 0
	s_add_u32 s84, s84, 0x100
	s_addc_u32 s85, s85, 0
	s_add_u32 s86, s86, 0x100
	s_addc_u32 s87, s87, 0
	s_cmp_gt_u32 s68, 13
	s_cbranch_scc0 .LBB0_943
	s_and_b64 vcc, exec, s[2:3]
	s_cbranch_vccz .LBB0_946
	s_barrier

; #define PG8_STAGE(bufoff, gbase, voff) do { _Pragma("unroll") for (int _i = 0; _i < 2; ++_i) { \
;         const unsigned _m0 = ldsu + (unsigned)(bufoff) + ldsw + (unsigned)(_i * 8192); \
;         asm volatile("s_mov_b32 m0, %2\n\ts_nop 0\n\tglobal_load_lds_dwordx4 %0, %1" :: "v"((voff)[_i]), "s"((const char*)(gbase)), "s"(_m0) : "memory"); } } while (0)
; #define PG8_LDA(dst, b, h) do { _Pragma("unroll") for (int m = 0; m < 4; ++m) _Pragma("unroll") for (int k = 0; k < 2; ++k) dst[m][k] = *(const LAS bf16x8*)(lds + PG8_SA(b, h) + aoff + m * 2048 + k * 1024); } while (0)
; #define PG8_LDB(dst, b, h) do { _Pragma("unroll") for (int n = 0; n < 2; ++n) _Pragma("unroll") for (int k = 0; k < 2; ++k) dst[n][k] = *(const LAS bf16x8*)(lds + bbase[b][h] + n * 2048 + k * 1024); } while (0)
; #define PG8_WAIT_V(n) asm volatile("s_waitcnt vmcnt(" #n ")" ::: "memory")
; #define PG8_WAIT_L(n) asm volatile("s_waitcnt lgkmcnt(" #n ")" ::: "memory")
; #define PG8_BAR __builtin_amdgcn_s_barrier()
; #define PG8_SCHED __builtin_amdgcn_sched_barrier(0)
; template <class Epi>
; __device__ __forceinline__ void gemm_phase(LAS unsigned char* lds, const Gemm g, const StaticOrder& S, const Epi& E) {
;     ...
;             const char* a2 = last ? nA : cA + (size_t)(t + 2) * kstep; const char* b2 = last ? nB : cB + (size_t)(t + 2) * kstep;
;             const char* a3 = a2 + kstep; const char* b3 = b2 + kstep;
;             const char* b1 = cB + (size_t)(t + 1) * kstep;
;             PG8_LDB(B0, 0, 0); PG8_SCHED; PG8_LDA(At, 0, 0); PG8_LDA(At2, 0, 1); PG8_STAGE(PG8_SB(1, 1), b1 + hstepB, voffB);
;             PG8_WAIT_V(8); PG8_WAIT_L(0); PG8_BAR; PG8_MMA2B(0, At, At2, B0); PG8_BAR; PG8_SCHED;
;             PG8_LDB(B0, 0, 1); PG8_STAGE(PG8_SB(0, 0), b2, voffB); PG8_STAGE(PG8_SA(0, 0), a2, voffA); PG8_STAGE(PG8_SA(0, 1), a2 + hstepA, voffA);
.LBB0_1027:
	ds_read_b128 v[68:71], v220
	ds_read_b128 v[84:87], v220 offset:1024
	ds_read_b128 v[88:91], v220 offset:2048
	ds_read_b128 v[92:95], v220 offset:3072
	s_add_u32 s12, s10, 0x100
	s_addc_u32 s13, s11, 0
	s_cmp_eq_u32 s69, 12
	s_cselect_b32 s14, s97, vcc_hi
	s_cselect_b32 s15, s7, s68
	s_cselect_b32 s84, vcc_lo, s12
	s_cselect_b32 s85, s39, s13
	s_add_u32 s16, s14, 0x80
	s_addc_u32 s17, s15, 0
	ds_read_b128 v[96:99], v221
	ds_read_b128 v[100:103], v221 offset:1024
	ds_read_b128 v[152:155], v221 offset:2048
	ds_read_b128 v[156:159], v221 offset:3072
	ds_read_b128 v[166:169], v221 offset:4096
	ds_read_b128 v[178:181], v221 offset:5120
	ds_read_b128 v[182:185], v221 offset:6144
	ds_read_b128 v[186:189], v221 offset:7168
	ds_read_b128 v[190:193], v221 offset:16384
	ds_read_b128 v[194:197], v221 offset:17408
	ds_read_b128 v[198:201], v221 offset:18432
	ds_read_b128 v[202:205], v221 offset:19456
	ds_read_b128 v[226:229], v221 offset:20480
	ds_read_b128 v[230:233], v221 offset:21504
	ds_read_b128 v[234:237], v221 offset:22528
	ds_read_b128 v[238:241], v221 offset:23552
	s_add_u32 s10, s10, 0x40080
	s_addc_u32 s11, s11, 0
	s_mov_b32 m0, s58
	s_nop 0
	global_load_lds_dwordx4 v217, s[10:11]
	s_mov_b32 m0, s60
	s_nop 0
	global_load_lds_dwordx4 v219, s[10:11]
	s_cmp_lg_u64 s[90:91], 0
	s_cbranch_scc1 .Lv8a_12
	s_waitcnt vmcnt(8)
.Lv8a_12:
	s_waitcnt lgkmcnt(0)
	s_barrier
	s_waitcnt lgkmcnt(14)
	v_mfma_f32_16x16x32_bf16 v[80:83], v[68:71], v[96:99], v[80:83]
	v_mfma_f32_16x16x32_bf16 v[76:79], v[88:91], v[96:99], v[76:79]
	s_waitcnt lgkmcnt(13)
	v_mfma_f32_16x16x32_bf16 v[148:151], v[68:71], v[152:155], v[148:151]
	v_mfma_f32_16x16x32_bf16 v[52:55], v[88:91], v[152:155], v[52:55]
	s_waitcnt lgkmcnt(11)
	v_mfma_f32_16x16x32_bf16 v[144:147], v[68:71], v[166:169], v[144:147]
	v_mfma_f32_16x16x32_bf16 v[48:51], v[88:91], v[166:169], v[48:51]
	s_waitcnt lgkmcnt(9)
	v_mfma_f32_16x16x32_bf16 v[136:139], v[68:71], v[182:185], v[136:139]
	v_mfma_f32_16x16x32_bf16 v[40:43], v[88:91], v[182:185], v[40:43]
	s_waitcnt lgkmcnt(7)
	v_mfma_f32_16x16x32_bf16 v[124:127], v[68:71], v[190:193], v[124:127]
	v_mfma_f32_16x16x32_bf16 v[28:31], v[88:91], v[190:193], v[28:31]
	s_waitcnt lgkmcnt(5)
	v_mfma_f32_16x16x32_bf16 v[120:123], v[68:71], v[198:201], v[120:123]
	v_mfma_f32_16x16x32_bf16 v[24:27], v[88:91], v[198:201], v[24:27]
	s_waitcnt lgkmcnt(3)
	v_mfma_f32_16x16x32_bf16 v[112:115], v[68:71], v[226:229], v[112:115]
	v_mfma_f32_16x16x32_bf16 v[16:19], v[88:91], v[226:229], v[16:19]
	s_waitcnt lgkmcnt(1)
	v_mfma_f32_16x16x32_bf16 v[64:67], v[68:71], v[234:237], v[64:67]
	v_mfma_f32_16x16x32_bf16 v[4:7], v[88:91], v[234:237], v[4:7]
	v_mfma_f32_16x16x32_bf16 v[80:83], v[84:87], v[100:103], v[80:83]
	v_mfma_f32_16x16x32_bf16 v[76:79], v[92:95], v[100:103], v[76:79]
	v_mfma_f32_16x16x32_bf16 v[148:151], v[84:87], v[156:159], v[148:151]
	v_mfma_f32_16x16x32_bf16 v[52:55], v[92:95], v[156:159], v[52:55]
	v_mfma_f32_16x16x32_bf16 v[144:147], v[84:87], v[178:181], v[144:147]
	v_mfma_f32_16x16x32_bf16 v[48:51], v[92:95], v[178:181], v[48:51]
	v_mfma_f32_16x16x32_bf16 v[136:139], v[84:87], v[186:189], v[136:139]
	v_mfma_f32_16x16x32_bf16 v[40:43], v[92:95], v[186:189], v[40:43]
	v_mfma_f32_16x16x32_bf16 v[124:127], v[84:87], v[194:197], v[124:127]
	v_mfma_f32_16x16x32_bf16 v[28:31], v[92:95], v[194:197], v[28:31]
	v_mfma_f32_16x16x32_bf16 v[120:123], v[84:87], v[202:205], v[120:123]
	v_mfma_f32_16x16x32_bf16 v[24:27], v[92:95], v[202:205], v[24:27]
	v_mfma_f32_16x16x32_bf16 v[112:115], v[84:87], v[230:233], v[112:115]
	v_mfma_f32_16x16x32_bf16 v[16:19], v[92:95], v[230:233], v[16:19]
	s_waitcnt lgkmcnt(0)
	v_mfma_f32_16x16x32_bf16 v[64:67], v[84:87], v[238:241], v[64:67]
	v_mfma_f32_16x16x32_bf16 v[4:7], v[92:95], v[238:241], v[4:7]
	s_cmp_eq_u64 s[90:91], 0
	s_cbranch_scc1 .Lv8b_12
	s_waitcnt vmcnt(8)
.Lv8b_12:
	s_barrier
	ds_read_b128 v[68:71], v222
	ds_read_b128 v[84:87], v222 offset:1024
	ds_read_b128 v[88:91], v222 offset:2048
	ds_read_b128 v[92:95], v222 offset:3072
	s_mov_b32 m0, s48
	s_nop 0
	global_load_lds_dwordx4 v217, s[84:85]
	s_mov_b32 m0, s49
	s_nop 0
	global_load_lds_dwordx4 v219, s[84:85]
	s_mov_b32 m0, s47
	s_nop 0
	global_load_lds_dwordx4 v216, s[14:15]
	s_mov_b32 m0, s50
	s_nop 0
	global_load_lds_dwordx4 v218, s[14:15]
	s_add_u32 s10, s14, 0x40000
	s_addc_u32 s11, s15, 0
	s_mov_b32 m0, s51
	s_nop 0
	global_load_lds_dwordx4 v216, s[10:11]
	s_mov_b32 m0, s52
	s_nop 0
	global_load_lds_dwordx4 v218, s[10:11]
	s_cmp_lg_u64 s[90:91], 0
	s_cbranch_scc1 .Lv8a_13
	s_waitcnt vmcnt(8)
; #define PG8_STAGE(bufoff, gbase, voff) do { _Pragma("unroll") for (int _i = 0; _i < 2; ++_i) { \
;         const unsigned _m0 = ldsu + (unsigned)(bufoff) + ldsw + (unsigned)(_i * 8192); \
;         asm volatile("s_mov_b32 m0, %2\n\ts_nop 0\n\tglobal_load_lds_dwordx4 %0, %1" :: "v"((voff)[_i]), "s"((const char*)(gbase)), "s"(_m0) : "memory"); } } while (0)
; #define PG8_LDA(dst, b, h) do { _Pragma("unroll") for (int m = 0; m < 4; ++m) _Pragma("unroll") for (int k = 0; k < 2; ++k) dst[m][k] = *(const LAS bf16x8*)(lds + PG8_SA(b, h) + aoff + m * 2048 + k * 1024); } while (0)
; #define PG8_LDB(dst, b, h) do { _Pragma("unroll") for (int n = 0; n < 2; ++n) _Pragma("unroll") for (int k = 0; k < 2; ++k) dst[n][k] = *(const LAS bf16x8*)(lds + bbase[b][h] + n * 2048 + k * 1024); } while (0)
; #define PG8_WAIT_V(n) asm volatile("s_waitcnt vmcnt(" #n ")" ::: "memory")
; #define PG8_WAIT_L(n) asm volatile("s_waitcnt lgkmcnt(" #n ")" ::: "memory")
; #define PG8_BAR __builtin_amdgcn_s_barrier()
; #define PG8_SCHED __builtin_amdgcn_sched_barrier(0)
; template <class Epi>
; __device__ __forceinline__ void gemm_phase(LAS unsigned char* lds, const Gemm g, const StaticOrder& S, const Epi& E) {
;     ...
;             PG8_WAIT_V(8); PG8_WAIT_L(0); PG8_BAR; PG8_MMA2B(1, At, At2, B0); PG8_BAR; PG8_SCHED;
;             PG8_LDB(B0, 1, 0); PG8_SCHED; PG8_LDA(At, 1, 0); PG8_LDA(At2, 1, 1); PG8_STAGE(PG8_SB(0, 1), b2 + hstepB, voffB);
;             PG8_WAIT_V(8); PG8_WAIT_L(0); PG8_BAR; PG8_MMA2B(0, At, At2, B0); PG8_BAR; PG8_SCHED;
.Lv8a_13:
	s_waitcnt lgkmcnt(0)
	s_barrier
	s_waitcnt lgkmcnt(3)
	v_mfma_f32_16x16x32_bf16 v[72:75], v[68:71], v[96:99], v[72:75]
	s_waitcnt lgkmcnt(1)
	v_mfma_f32_16x16x32_bf16 v[56:59], v[88:91], v[96:99], v[56:59]
	v_mfma_f32_16x16x32_bf16 v[44:47], v[88:91], v[152:155], v[44:47]
	v_mfma_f32_16x16x32_bf16 v[36:39], v[88:91], v[166:169], v[36:39]
	v_mfma_f32_16x16x32_bf16 v[128:131], v[68:71], v[182:185], v[128:131]
	v_mfma_f32_16x16x32_bf16 v[32:35], v[88:91], v[182:185], v[32:35]
	v_mfma_f32_16x16x32_bf16 v[116:119], v[68:71], v[190:193], v[116:119]
	v_mfma_f32_16x16x32_bf16 v[20:23], v[88:91], v[190:193], v[20:23]
	v_mfma_f32_16x16x32_bf16 v[108:111], v[68:71], v[198:201], v[108:111]
	v_mfma_f32_16x16x32_bf16 v[12:15], v[88:91], v[198:201], v[12:15]
	v_mfma_f32_16x16x32_bf16 v[104:107], v[68:71], v[226:229], v[104:107]
	v_mfma_f32_16x16x32_bf16 v[8:11], v[88:91], v[226:229], v[8:11]
	v_mfma_f32_16x16x32_bf16 v[60:63], v[68:71], v[234:237], v[60:63]
	v_mfma_f32_16x16x32_bf16 v[0:3], v[88:91], v[234:237], v[0:3]
	v_mfma_f32_16x16x32_bf16 v[72:75], v[84:87], v[100:103], v[72:75]
	s_waitcnt lgkmcnt(0)
	v_mfma_f32_16x16x32_bf16 v[56:59], v[92:95], v[100:103], v[56:59]
	v_mfma_f32_16x16x32_bf16 v[96:99], v[68:71], v[152:155], v[140:143]
	v_mfma_f32_16x16x32_bf16 v[44:47], v[92:95], v[156:159], v[44:47]
	v_mfma_f32_16x16x32_bf16 v[100:103], v[68:71], v[166:169], v[132:135]
	v_mfma_f32_16x16x32_bf16 v[36:39], v[92:95], v[178:181], v[36:39]
	v_mfma_f32_16x16x32_bf16 v[128:131], v[84:87], v[186:189], v[128:131]
	v_mfma_f32_16x16x32_bf16 v[32:35], v[92:95], v[186:189], v[32:35]
	v_mfma_f32_16x16x32_bf16 v[116:119], v[84:87], v[194:197], v[116:119]
	v_mfma_f32_16x16x32_bf16 v[20:23], v[92:95], v[194:197], v[20:23]
	v_mfma_f32_16x16x32_bf16 v[108:111], v[84:87], v[202:205], v[108:111]
	v_mfma_f32_16x16x32_bf16 v[12:15], v[92:95], v[202:205], v[12:15]
	v_mfma_f32_16x16x32_bf16 v[104:107], v[84:87], v[230:233], v[104:107]
	v_mfma_f32_16x16x32_bf16 v[8:11], v[92:95], v[230:233], v[8:11]
	v_mfma_f32_16x16x32_bf16 v[60:63], v[84:87], v[238:241], v[60:63]
	v_mfma_f32_16x16x32_bf16 v[0:3], v[92:95], v[238:241], v[0:3]
	v_mfma_f32_16x16x32_bf16 v[96:99], v[84:87], v[156:159], v[96:99]
	v_mfma_f32_16x16x32_bf16 v[100:103], v[84:87], v[178:181], v[100:103]
	s_cmp_eq_u64 s[90:91], 0
	s_cbranch_scc1 .Lv8b_13
	s_waitcnt vmcnt(8)
.Lv8b_13:
	s_barrier
	ds_read_b128 v[68:71], v223
	ds_read_b128 v[84:87], v223 offset:1024
	ds_read_b128 v[88:91], v223 offset:2048
	ds_read_b128 v[92:95], v223 offset:3072
	ds_read_b128 v[132:135], v221 offset:32768
	ds_read_b128 v[140:143], v221 offset:33792
	ds_read_b128 v[152:155], v221 offset:34816
	ds_read_b128 v[156:159], v221 offset:35840
	ds_read_b128 v[166:169], v221 offset:36864
	ds_read_b128 v[178:181], v221 offset:37888
	ds_read_b128 v[182:185], v221 offset:38912
	ds_read_b128 v[186:189], v221 offset:39936
	ds_read_b128 v[190:193], v221 offset:49152
	ds_read_b128 v[194:197], v221 offset:50176
	ds_read_b128 v[198:201], v221 offset:51200
	ds_read_b128 v[202:205], v221 offset:52224
	ds_read_b128 v[226:229], v221 offset:53248
	ds_read_b128 v[230:233], v221 offset:54272
	ds_read_b128 v[234:237], v221 offset:55296
	ds_read_b128 v[238:241], v221 offset:56320
	s_add_u32 s10, s84, 0x40000
	s_addc_u32 s11, s85, 0
	s_mov_b32 m0, s53
	s_nop 0
	global_load_lds_dwordx4 v217, s[10:11]
	s_mov_b32 m0, s54
	s_nop 0
	global_load_lds_dwordx4 v219, s[10:11]
	s_cmp_lg_u64 s[90:91], 0
	s_cbranch_scc1 .Lv8a_14
	s_waitcnt vmcnt(8)
.Lv8a_14:
	s_waitcnt lgkmcnt(0)
	s_barrier
	s_waitcnt lgkmcnt(14)
	v_mfma_f32_16x16x32_bf16 v[80:83], v[68:71], v[132:135], v[80:83]
	v_mfma_f32_16x16x32_bf16 v[76:79], v[88:91], v[132:135], v[76:79]
	s_waitcnt lgkmcnt(13)
	v_mfma_f32_16x16x32_bf16 v[148:151], v[68:71], v[152:155], v[148:151]
	v_mfma_f32_16x16x32_bf16 v[52:55], v[88:91], v[152:155], v[52:55]
	s_waitcnt lgkmcnt(11)
	v_mfma_f32_16x16x32_bf16 v[144:147], v[68:71], v[166:169], v[144:147]
	v_mfma_f32_16x16x32_bf16 v[48:51], v[88:91], v[166:169], v[48:51]
	s_waitcnt lgkmcnt(9)
	v_mfma_f32_16x16x32_bf16 v[136:139], v[68:71], v[182:185], v[136:139]
	v_mfma_f32_16x16x32_bf16 v[40:43], v[88:91], v[182:185], v[40:43]
	s_waitcnt lgkmcnt(7)
	v_mfma_f32_16x16x32_bf16 v[124:127], v[68:71], v[190:193], v[124:127]
	v_mfma_f32_16x16x32_bf16 v[28:31], v[88:91], v[190:193], v[28:31]
	s_waitcnt lgkmcnt(5)
	v_mfma_f32_16x16x32_bf16 v[120:123], v[68:71], v[198:201], v[120:123]
	v_mfma_f32_16x16x32_bf16 v[24:27], v[88:91], v[198:201], v[24:27]
	s_waitcnt lgkmcnt(3)
	v_mfma_f32_16x16x32_bf16 v[112:115], v[68:71], v[226:229], v[112:115]
	v_mfma_f32_16x16x32_bf16 v[16:19], v[88:91], v[226:229], v[16:19]
	s_waitcnt lgkmcnt(1)
	v_mfma_f32_16x16x32_bf16 v[64:67], v[68:71], v[234:237], v[64:67]
	v_mfma_f32_16x16x32_bf16 v[4:7], v[88:91], v[234:237], v[4:7]
	v_mfma_f32_16x16x32_bf16 v[80:83], v[84:87], v[140:143], v[80:83]
	v_mfma_f32_16x16x32_bf16 v[76:79], v[92:95], v[140:143], v[76:79]
	v_mfma_f32_16x16x32_bf16 v[148:151], v[84:87], v[156:159], v[148:151]
	v_mfma_f32_16x16x32_bf16 v[52:55], v[92:95], v[156:159], v[52:55]
	v_mfma_f32_16x16x32_bf16 v[144:147], v[84:87], v[178:181], v[144:147]
	v_mfma_f32_16x16x32_bf16 v[48:51], v[92:95], v[178:181], v[48:51]
	v_mfma_f32_16x16x32_bf16 v[136:139], v[84:87], v[186:189], v[136:139]
	v_mfma_f32_16x16x32_bf16 v[40:43], v[92:95], v[186:189], v[40:43]
	v_mfma_f32_16x16x32_bf16 v[124:127], v[84:87], v[194:197], v[124:127]
	v_mfma_f32_16x16x32_bf16 v[28:31], v[92:95], v[194:197], v[28:31]
	v_mfma_f32_16x16x32_bf16 v[120:123], v[84:87], v[202:205], v[120:123]
	v_mfma_f32_16x16x32_bf16 v[24:27], v[92:95], v[202:205], v[24:27]
	v_mfma_f32_16x16x32_bf16 v[112:115], v[84:87], v[230:233], v[112:115]
	v_mfma_f32_16x16x32_bf16 v[16:19], v[92:95], v[230:233], v[16:19]
	s_waitcnt lgkmcnt(0)
	v_mfma_f32_16x16x32_bf16 v[64:67], v[84:87], v[238:241], v[64:67]
	v_mfma_f32_16x16x32_bf16 v[4:7], v[92:95], v[238:241], v[4:7]
	s_cmp_eq_u64 s[90:91], 0
	s_cbranch_scc1 .Lv8b_14
	s_waitcnt vmcnt(8)
; #define PG8_STAGE(bufoff, gbase, voff) do { _Pragma("unroll") for (int _i = 0; _i < 2; ++_i) { \
;         const unsigned _m0 = ldsu + (unsigned)(bufoff) + ldsw + (unsigned)(_i * 8192); \
;         asm volatile("s_mov_b32 m0, %2\n\ts_nop 0\n\tglobal_load_lds_dwordx4 %0, %1" :: "v"((voff)[_i]), "s"((const char*)(gbase)), "s"(_m0) : "memory"); } } while (0)
; #define PG8_LDB(dst, b, h) do { _Pragma("unroll") for (int n = 0; n < 2; ++n) _Pragma("unroll") for (int k = 0; k < 2; ++k) dst[n][k] = *(const LAS bf16x8*)(lds + bbase[b][h] + n * 2048 + k * 1024); } while (0)
; #define PG8_WAIT_V(n) asm volatile("s_waitcnt vmcnt(" #n ")" ::: "memory")
; #define PG8_WAIT_L(n) asm volatile("s_waitcnt lgkmcnt(" #n ")" ::: "memory")
; #define PG8_BAR __builtin_amdgcn_s_barrier()
; #define PG8_SCHED __builtin_amdgcn_sched_barrier(0)
; template <class Epi>
; __device__ __forceinline__ void gemm_phase(LAS unsigned char* lds, const Gemm g, const StaticOrder& S, const Epi& E) {
;     ...
;             PG8_LDB(B0, 1, 1); PG8_STAGE(PG8_SB(1, 0), b3, voffB); PG8_STAGE(PG8_SA(1, 0), a3, voffA); PG8_STAGE(PG8_SA(1, 1), a3 + hstepA, voffA);
;             PG8_WAIT_V(8); PG8_WAIT_L(0); PG8_BAR; PG8_MMA2B(1, At, At2, B0); PG8_BAR; PG8_SCHED;
;         }
;         if (wr == 0) PG8_BAR;
;     __device__ __forceinline__ void operator()(f32x4 (&acc)[2][2][4][2], const Unit& u, int wr, int wc, int fr, int fq) const {
;     ...
;           if (wr == 0) { const float* sp = ssq + ((size_t)u.pm * 256 + t) * 16; const f32x4 a = *(const f32x4*)sp, b = *(const f32x4*)(sp + 4), c = *(const f32x4*)(sp + 8), d = *(const f32x4*)(sp + 12);
.Lv8b_14:
	s_barrier
	s_add_u32 s10, s84, 0x80
	ds_read_b128 v[68:71], v224
	ds_read_b128 v[84:87], v224 offset:1024
	ds_read_b128 v[88:91], v224 offset:2048
	ds_read_b128 v[92:95], v224 offset:3072
	s_addc_u32 s11, s85, 0
	s_mov_b32 m0, s88
	s_nop 0
	global_load_lds_dwordx4 v217, s[10:11]
	s_mov_b32 m0, s89
	s_nop 0
	global_load_lds_dwordx4 v219, s[10:11]
	s_mov_b32 m0, s95
	s_nop 0
	global_load_lds_dwordx4 v216, s[16:17]
	s_mov_b32 m0, s37
	s_nop 0
	global_load_lds_dwordx4 v218, s[16:17]
	s_add_u32 s10, s14, 0x40080
	s_addc_u32 s11, s15, 0
	s_mov_b32 m0, s56
	s_nop 0
	global_load_lds_dwordx4 v216, s[10:11]
	s_mov_b32 m0, s57
	s_nop 0
	global_load_lds_dwordx4 v218, s[10:11]
	s_cmp_lg_u64 s[90:91], 0
	s_cbranch_scc1 .Lv8a_15
	s_waitcnt vmcnt(8)
.Lv8a_15:
	s_waitcnt lgkmcnt(0)
	s_barrier
	s_waitcnt lgkmcnt(3)
	v_mfma_f32_16x16x32_bf16 v[72:75], v[68:71], v[132:135], v[72:75]
	s_waitcnt lgkmcnt(1)
	v_mfma_f32_16x16x32_bf16 v[56:59], v[88:91], v[132:135], v[56:59]
	v_mfma_f32_16x16x32_bf16 v[96:99], v[68:71], v[152:155], v[96:99]
	v_mfma_f32_16x16x32_bf16 v[72:75], v[84:87], v[140:143], v[72:75]
	s_waitcnt lgkmcnt(0)
	v_mfma_f32_16x16x32_bf16 v[56:59], v[92:95], v[140:143], v[56:59]
	v_mfma_f32_16x16x32_bf16 v[140:143], v[84:87], v[156:159], v[96:99]
	v_mfma_f32_16x16x32_bf16 v[96:99], v[68:71], v[166:169], v[100:103]
	v_mfma_f32_16x16x32_bf16 v[132:135], v[84:87], v[178:181], v[96:99]
	v_mfma_f32_16x16x32_bf16 v[96:99], v[68:71], v[182:185], v[128:131]
	v_mfma_f32_16x16x32_bf16 v[128:131], v[84:87], v[186:189], v[96:99]
	v_mfma_f32_16x16x32_bf16 v[96:99], v[68:71], v[190:193], v[116:119]
	v_mfma_f32_16x16x32_bf16 v[116:119], v[84:87], v[194:197], v[96:99]
	v_mfma_f32_16x16x32_bf16 v[96:99], v[68:71], v[198:201], v[108:111]
	v_mfma_f32_16x16x32_bf16 v[44:47], v[88:91], v[152:155], v[44:47]
	v_mfma_f32_16x16x32_bf16 v[36:39], v[88:91], v[166:169], v[36:39]
	v_mfma_f32_16x16x32_bf16 v[32:35], v[88:91], v[182:185], v[32:35]
	v_mfma_f32_16x16x32_bf16 v[20:23], v[88:91], v[190:193], v[20:23]
	v_mfma_f32_16x16x32_bf16 v[108:111], v[84:87], v[202:205], v[96:99]
	v_mfma_f32_16x16x32_bf16 v[12:15], v[88:91], v[198:201], v[12:15]
	v_mfma_f32_16x16x32_bf16 v[96:99], v[68:71], v[226:229], v[104:107]
	v_mfma_f32_16x16x32_bf16 v[8:11], v[88:91], v[226:229], v[8:11]
	v_mfma_f32_16x16x32_bf16 v[60:63], v[68:71], v[234:237], v[60:63]
	v_mfma_f32_16x16x32_bf16 v[0:3], v[88:91], v[234:237], v[0:3]
	v_mfma_f32_16x16x32_bf16 v[44:47], v[92:95], v[156:159], v[44:47]
	v_mfma_f32_16x16x32_bf16 v[36:39], v[92:95], v[178:181], v[36:39]
	v_mfma_f32_16x16x32_bf16 v[32:35], v[92:95], v[186:189], v[32:35]
	v_mfma_f32_16x16x32_bf16 v[20:23], v[92:95], v[194:197], v[20:23]
	v_mfma_f32_16x16x32_bf16 v[12:15], v[92:95], v[202:205], v[12:15]
	v_mfma_f32_16x16x32_bf16 v[104:107], v[84:87], v[230:233], v[96:99]
	v_mfma_f32_16x16x32_bf16 v[8:11], v[92:95], v[230:233], v[8:11]
	v_mfma_f32_16x16x32_bf16 v[60:63], v[84:87], v[238:241], v[60:63]
	v_mfma_f32_16x16x32_bf16 v[0:3], v[92:95], v[238:241], v[0:3]
	s_cmp_eq_u64 s[90:91], 0
	s_cbranch_scc1 .Lv8b_15
	s_waitcnt vmcnt(8)
.Lv8b_15:
	s_barrier
	s_add_i32 s69, s69, 2
	s_add_u32 vcc_hi, vcc_hi, 0x100
	s_addc_u32 s68, s68, 0
	s_cmp_gt_u32 s69, 13
	s_mov_b64 s[10:11], s[12:13]
	s_cbranch_scc0 .LBB0_1027
	s_and_b64 vcc, exec, s[90:91]
	s_cbranch_vccz .LBB0_1030
	v_lshlrev_b32_e32 v68, 4, v215
	v_add3_u32 v68, v214, s59, v68
	s_ashr_i32 s97, s96, 31
	s_lshl_b64 s[12:13], s[96:97], 14
	v_ashrrev_i32_e32 v69, 31, v68
	s_add_u32 s12, s18, s12
	s_addc_u32 s13, s19, s13
	v_lshlrev_b64 v[70:71], 6, v[68:69]
	v_lshl_add_u64 v[70:71], s[12:13], 0, v[70:71]
	global_load_dwordx4 v[86:89], v[70:71], off
	global_load_dwordx4 v[90:93], v[70:71], off offset:16
	global_load_dwordx4 v[94:97], v[70:71], off offset:32
	global_load_dwordx4 v[98:101], v[70:71], off offset:48
	s_barrier

; #define PG8_STAGE(bufoff, gbase, voff) do { _Pragma("unroll") for (int _i = 0; _i < 2; ++_i) { \
;         const unsigned _m0 = ldsu + (unsigned)(bufoff) + ldsw + (unsigned)(_i * 8192); \
;         asm volatile("s_mov_b32 m0, %2\n\ts_nop 0\n\tglobal_load_lds_dwordx4 %0, %1" :: "v"((voff)[_i]), "s"((const char*)(gbase)), "s"(_m0) : "memory"); } } while (0)
; #define PG8_LDA(dst, b, h) do { _Pragma("unroll") for (int m = 0; m < 4; ++m) _Pragma("unroll") for (int k = 0; k < 2; ++k) dst[m][k] = *(const LAS bf16x8*)(lds + PG8_SA(b, h) + aoff + m * 2048 + k * 1024); } while (0)
; #define PG8_LDB(dst, b, h) do { _Pragma("unroll") for (int n = 0; n < 2; ++n) _Pragma("unroll") for (int k = 0; k < 2; ++k) dst[n][k] = *(const LAS bf16x8*)(lds + bbase[b][h] + n * 2048 + k * 1024); } while (0)
; #define PG8_WAIT_V(n) asm volatile("s_waitcnt vmcnt(" #n ")" ::: "memory")
; #define PG8_WAIT_L(n) asm volatile("s_waitcnt lgkmcnt(" #n ")" ::: "memory")
; #define PG8_BAR __builtin_amdgcn_s_barrier()
; #define PG8_SCHED __builtin_amdgcn_sched_barrier(0)
; template <class Epi>
; __device__ __forceinline__ void gemm_phase(LAS unsigned char* lds, const Gemm g, const StaticOrder& S, const Epi& E) {
;     ...
;             const bool last = (t == nt - 2);
;             const char* a2 = last ? nA : cA + (size_t)(t + 2) * kstep; const char* b2 = last ? nB : cB + (size_t)(t + 2) * kstep;
;             const char* a3 = a2 + kstep; const char* b3 = b2 + kstep;
;             const char* b1 = cB + (size_t)(t + 1) * kstep;
;             PG8_LDB(B0, 0, 0); PG8_SCHED; PG8_LDA(At, 0, 0); PG8_LDA(At2, 0, 1); PG8_STAGE(PG8_SB(1, 1), b1 + hstepB, voffB);
;             PG8_WAIT_V(8); PG8_WAIT_L(0); PG8_BAR; PG8_MMA2B(0, At, At2, B0); PG8_BAR; PG8_SCHED;
.LBB0_1140:
	ds_read_b128 v[128:131], v138
	ds_read_b128 v[144:147], v138 offset:1024
	ds_read_b128 v[148:151], v138 offset:2048
	ds_read_b128 v[152:155], v138 offset:3072
	s_cmp_eq_u32 s68, 40
	s_cselect_b32 s14, s4, s80
	s_cselect_b32 s15, s5, s81
	s_cselect_b32 s42, s10, s82
	s_cselect_b32 s43, s11, s83
	s_add_u32 s16, s14, 0x80
	s_addc_u32 s17, s15, 0
	s_add_u32 s38, s42, 0x80
	s_addc_u32 s39, s43, 0
	ds_read_b128 v[156:159], v139
	ds_read_b128 v[166:169], v139 offset:1024
	ds_read_b128 v[178:181], v139 offset:2048
	ds_read_b128 v[182:185], v139 offset:3072
	ds_read_b128 v[186:189], v139 offset:4096
	ds_read_b128 v[190:193], v139 offset:5120
	ds_read_b128 v[194:197], v139 offset:6144
	ds_read_b128 v[198:201], v139 offset:7168
	ds_read_b128 v[202:205], v139 offset:16384
	ds_read_b128 v[214:217], v139 offset:17408
	ds_read_b128 v[218:221], v139 offset:18432
	ds_read_b128 v[222:225], v139 offset:19456
	ds_read_b128 v[226:229], v139 offset:20480
	ds_read_b128 v[230:233], v139 offset:21504
	ds_read_b128 v[234:237], v139 offset:22528
	ds_read_b128 v[238:241], v139 offset:23552
	s_mov_b32 m0, s61
	s_nop 0
	global_load_lds_dwordx4 v133, s[12:13]
	s_mov_b32 m0, s63
	s_nop 0
	global_load_lds_dwordx4 v135, s[12:13]
	s_cmp_lg_u64 s[2:3], 0
	s_cbranch_scc1 .Lv8a_16
	s_waitcnt vmcnt(8)

; #define PG8_STAGE(bufoff, gbase, voff) do { _Pragma("unroll") for (int _i = 0; _i < 2; ++_i) { \
;         const unsigned _m0 = ldsu + (unsigned)(bufoff) + ldsw + (unsigned)(_i * 8192); \
;         asm volatile("s_mov_b32 m0, %2\n\ts_nop 0\n\tglobal_load_lds_dwordx4 %0, %1" :: "v"((voff)[_i]), "s"((const char*)(gbase)), "s"(_m0) : "memory"); } } while (0)
; #define PG8_LDB(dst, b, h) do { _Pragma("unroll") for (int n = 0; n < 2; ++n) _Pragma("unroll") for (int k = 0; k < 2; ++k) dst[n][k] = *(const LAS bf16x8*)(lds + bbase[b][h] + n * 2048 + k * 1024); } while (0)
; #define PG8_WAIT_V(n) asm volatile("s_waitcnt vmcnt(" #n ")" ::: "memory")
; #define PG8_WAIT_L(n) asm volatile("s_waitcnt lgkmcnt(" #n ")" ::: "memory")
; #define PG8_BAR __builtin_amdgcn_s_barrier()
; #define PG8_SCHED __builtin_amdgcn_sched_barrier(0)
; template <class Epi>
; __device__ __forceinline__ void gemm_phase(LAS unsigned char* lds, const Gemm g, const StaticOrder& S, const Epi& E) {
;     ...
;             PG8_LDB(B0, 0, 1); PG8_STAGE(PG8_SB(0, 0), b2, voffB); PG8_STAGE(PG8_SA(0, 0), a2, voffA); PG8_STAGE(PG8_SA(0, 1), a2 + hstepA, voffA);
;             PG8_WAIT_V(8); PG8_WAIT_L(0); PG8_BAR; PG8_MMA2B(1, At, At2, B0); PG8_BAR; PG8_SCHED;
.Lv8b_16:
	s_barrier
	ds_read_b128 v[128:131], v140
	ds_read_b128 v[144:147], v140 offset:1024
	ds_read_b128 v[148:151], v140 offset:2048
	ds_read_b128 v[152:155], v140 offset:3072
	s_mov_b32 m0, s48
	s_nop 0
	global_load_lds_dwordx4 v133, s[42:43]
	s_mov_b32 m0, s49
	s_nop 0
	global_load_lds_dwordx4 v135, s[42:43]
	s_mov_b32 m0, s47
	s_nop 0
	global_load_lds_dwordx4 v132, s[14:15]
	s_mov_b32 m0, s50
	s_nop 0
	global_load_lds_dwordx4 v134, s[14:15]
	s_add_u32 s84, s14, 0xb0000
	s_addc_u32 s85, s15, 0
	s_mov_b32 m0, s51
	s_nop 0
	global_load_lds_dwordx4 v132, s[84:85]
	s_mov_b32 m0, s52
	s_nop 0
	global_load_lds_dwordx4 v134, s[84:85]
	s_cmp_lg_u64 s[2:3], 0
	s_cbranch_scc1 .Lv8a_17
	s_waitcnt vmcnt(8)

; #define PG8_STAGE(bufoff, gbase, voff) do { _Pragma("unroll") for (int _i = 0; _i < 2; ++_i) { \
;         const unsigned _m0 = ldsu + (unsigned)(bufoff) + ldsw + (unsigned)(_i * 8192); \
;         asm volatile("s_mov_b32 m0, %2\n\ts_nop 0\n\tglobal_load_lds_dwordx4 %0, %1" :: "v"((voff)[_i]), "s"((const char*)(gbase)), "s"(_m0) : "memory"); } } while (0)
; #define PG8_LDA(dst, b, h) do { _Pragma("unroll") for (int m = 0; m < 4; ++m) _Pragma("unroll") for (int k = 0; k < 2; ++k) dst[m][k] = *(const LAS bf16x8*)(lds + PG8_SA(b, h) + aoff + m * 2048 + k * 1024); } while (0)
; #define PG8_LDB(dst, b, h) do { _Pragma("unroll") for (int n = 0; n < 2; ++n) _Pragma("unroll") for (int k = 0; k < 2; ++k) dst[n][k] = *(const LAS bf16x8*)(lds + bbase[b][h] + n * 2048 + k * 1024); } while (0)
; #define PG8_WAIT_V(n) asm volatile("s_waitcnt vmcnt(" #n ")" ::: "memory")
; #define PG8_WAIT_L(n) asm volatile("s_waitcnt lgkmcnt(" #n ")" ::: "memory")
; #define PG8_BAR __builtin_amdgcn_s_barrier()
; #define PG8_SCHED __builtin_amdgcn_sched_barrier(0)
; template <class Epi>
; __device__ __forceinline__ void gemm_phase(LAS unsigned char* lds, const Gemm g, const StaticOrder& S, const Epi& E) {
;     ...
;             PG8_LDB(B0, 1, 0); PG8_SCHED; PG8_LDA(At, 1, 0); PG8_LDA(At2, 1, 1); PG8_STAGE(PG8_SB(0, 1), b2 + hstepB, voffB);
;             PG8_WAIT_V(8); PG8_WAIT_L(0); PG8_BAR; PG8_MMA2B(0, At, At2, B0); PG8_BAR; PG8_SCHED;
.Lv8b_17:
	s_barrier
	ds_read_b128 v[128:131], v141
	ds_read_b128 v[144:147], v141 offset:1024
	ds_read_b128 v[148:151], v141 offset:2048
	ds_read_b128 v[152:155], v141 offset:3072
	ds_read_b128 v[156:159], v139 offset:32768
	ds_read_b128 v[166:169], v139 offset:33792
	ds_read_b128 v[178:181], v139 offset:34816
	ds_read_b128 v[182:185], v139 offset:35840
	ds_read_b128 v[186:189], v139 offset:36864
	ds_read_b128 v[190:193], v139 offset:37888
	ds_read_b128 v[194:197], v139 offset:38912
	ds_read_b128 v[198:201], v139 offset:39936
	ds_read_b128 v[202:205], v139 offset:49152
	ds_read_b128 v[214:217], v139 offset:50176
	ds_read_b128 v[218:221], v139 offset:51200
	ds_read_b128 v[222:225], v139 offset:52224
	ds_read_b128 v[226:229], v139 offset:53248
	ds_read_b128 v[230:233], v139 offset:54272
	ds_read_b128 v[234:237], v139 offset:55296
	ds_read_b128 v[238:241], v139 offset:56320
	s_add_u32 s42, s42, 0xb0000
	s_addc_u32 s43, s43, 0
	s_mov_b32 m0, s53
	s_nop 0
	global_load_lds_dwordx4 v133, s[42:43]
	s_mov_b32 m0, s54
	s_nop 0
	global_load_lds_dwordx4 v135, s[42:43]
	s_cmp_lg_u64 s[2:3], 0
	s_cbranch_scc1 .Lv8a_18
	s_waitcnt vmcnt(8)

; #define PG8_STAGE(bufoff, gbase, voff) do { _Pragma("unroll") for (int _i = 0; _i < 2; ++_i) { \
;         const unsigned _m0 = ldsu + (unsigned)(bufoff) + ldsw + (unsigned)(_i * 8192); \
;         asm volatile("s_mov_b32 m0, %2\n\ts_nop 0\n\tglobal_load_lds_dwordx4 %0, %1" :: "v"((voff)[_i]), "s"((const char*)(gbase)), "s"(_m0) : "memory"); } } while (0)
; #define PG8_LDB(dst, b, h) do { _Pragma("unroll") for (int n = 0; n < 2; ++n) _Pragma("unroll") for (int k = 0; k < 2; ++k) dst[n][k] = *(const LAS bf16x8*)(lds + bbase[b][h] + n * 2048 + k * 1024); } while (0)
; #define PG8_WAIT_V(n) asm volatile("s_waitcnt vmcnt(" #n ")" ::: "memory")
; #define PG8_WAIT_L(n) asm volatile("s_waitcnt lgkmcnt(" #n ")" ::: "memory")
; #define PG8_BAR __builtin_amdgcn_s_barrier()
; #define PG8_SCHED __builtin_amdgcn_sched_barrier(0)
; template <class Epi>
; __device__ __forceinline__ void gemm_phase(LAS unsigned char* lds, const Gemm g, const StaticOrder& S, const Epi& E) {
;     ...
;             PG8_LDB(B0, 1, 1); PG8_STAGE(PG8_SB(1, 0), b3, voffB); PG8_STAGE(PG8_SA(1, 0), a3, voffA); PG8_STAGE(PG8_SA(1, 1), a3 + hstepA, voffA);
;             PG8_WAIT_V(8); PG8_WAIT_L(0); PG8_BAR; PG8_MMA2B(1, At, At2, B0); PG8_BAR; PG8_SCHED;
.Lv8b_18:
	s_barrier
	ds_read_b128 v[128:131], v142
	ds_read_b128 v[144:147], v142 offset:1024
	ds_read_b128 v[148:151], v142 offset:2048
	ds_read_b128 v[152:155], v142 offset:3072
	s_mov_b32 m0, s55
	s_nop 0
	global_load_lds_dwordx4 v133, s[38:39]
	s_mov_b32 m0, s56
	s_nop 0
	global_load_lds_dwordx4 v135, s[38:39]
	s_mov_b32 m0, s57
	s_nop 0
	global_load_lds_dwordx4 v132, s[16:17]
	s_mov_b32 m0, s58
	s_nop 0
	global_load_lds_dwordx4 v134, s[16:17]
	s_add_u32 s14, s14, 0xb0080
	s_addc_u32 s15, s15, 0
	s_mov_b32 m0, s59
	s_nop 0
	global_load_lds_dwordx4 v132, s[14:15]
	s_mov_b32 m0, s60
	s_nop 0
	global_load_lds_dwordx4 v134, s[14:15]
	s_cmp_lg_u64 s[2:3], 0
	s_cbranch_scc1 .Lv8a_19
	s_waitcnt vmcnt(8)

; #define PG8_STAGE(bufoff, gbase, voff) do { _Pragma("unroll") for (int _i = 0; _i < 2; ++_i) { \
;         const unsigned _m0 = ldsu + (unsigned)(bufoff) + ldsw + (unsigned)(_i * 8192); \
;         asm volatile("s_mov_b32 m0, %2\n\ts_nop 0\n\tglobal_load_lds_dwordx4 %0, %1" :: "v"((voff)[_i]), "s"((const char*)(gbase)), "s"(_m0) : "memory"); } } while (0)
; #define PG8_LDA(dst, b, h) do { _Pragma("unroll") for (int m = 0; m < 4; ++m) _Pragma("unroll") for (int k = 0; k < 2; ++k) dst[m][k] = *(const LAS bf16x8*)(lds + PG8_SA(b, h) + aoff + m * 2048 + k * 1024); } while (0)
; #define PG8_LDB(dst, b, h) do { _Pragma("unroll") for (int n = 0; n < 2; ++n) _Pragma("unroll") for (int k = 0; k < 2; ++k) dst[n][k] = *(const LAS bf16x8*)(lds + bbase[b][h] + n * 2048 + k * 1024); } while (0)
; #define PG8_WAIT_V(n) asm volatile("s_waitcnt vmcnt(" #n ")" ::: "memory")
; template <class Epi>
; __device__ __forceinline__ void gemm_phase(LAS unsigned char* lds, const Gemm g, const StaticOrder& S, const Epi& E) {
;     ...
;         for (int t = 0; t < nt; t += 2) {
;             const bool last = (t == nt - 2);
;             const char* a2 = last ? nA : cA + (size_t)(t + 2) * kstep; const char* b2 = last ? nB : cB + (size_t)(t + 2) * kstep;
;             const char* a3 = a2 + kstep; const char* b3 = b2 + kstep;
;             const char* b1 = cB + (size_t)(t + 1) * kstep;
;             PG8_LDB(B0, 0, 0); PG8_SCHED; PG8_LDA(At, 0, 0); PG8_LDA(At2, 0, 1); PG8_STAGE(PG8_SB(1, 1), b1 + hstepB, voffB);
;             PG8_WAIT_V(8); PG8_WAIT_L(0); PG8_BAR; PG8_MMA2B(0, At, At2, B0); PG8_BAR; PG8_SCHED;
;             PG8_LDB(B0, 0, 1); PG8_STAGE(PG8_SB(0, 0), b2, voffB); PG8_STAGE(PG8_SA(0, 0), a2, voffA); PG8_STAGE(PG8_SA(0, 1), a2 + hstepA, voffA);
;             PG8_WAIT_V(8); PG8_WAIT_L(0); PG8_BAR; PG8_MMA2B(1, At, At2, B0); PG8_BAR; PG8_SCHED;
;             PG8_LDB(B0, 1, 0); PG8_SCHED; PG8_LDA(At, 1, 0); PG8_LDA(At2, 1, 1); PG8_STAGE(PG8_SB(0, 1), b2 + hstepB, voffB);
;             PG8_WAIT_V(8); PG8_WAIT_L(0); PG8_BAR; PG8_MMA2B(0, At, At2, B0); PG8_BAR; PG8_SCHED;
;             PG8_LDB(B0, 1, 1); PG8_STAGE(PG8_SB(1, 0), b3, voffB); PG8_STAGE(PG8_SA(1, 0), a3, voffA); PG8_STAGE(PG8_SA(1, 1), a3 + hstepA, voffA);
;             PG8_WAIT_V(8); PG8_WAIT_L(0); PG8_BAR; PG8_MMA2B(1, At, At2, B0); PG8_BAR; PG8_SCHED;
;         }
;         if (wr == 0) PG8_BAR;
.Lv8b_19:
	s_barrier
	s_add_i32 s68, s68, 2
	s_add_u32 s12, s12, 0x100
	s_addc_u32 s13, s13, 0
	s_add_u32 s80, s80, 0x100
	s_addc_u32 s81, s81, 0
	s_add_u32 s82, s82, 0x100
	s_addc_u32 s83, s83, 0
	s_cmp_gt_u32 s68, 41
	s_cbranch_scc0 .LBB0_1140
	s_and_b64 vcc, exec, s[2:3]
	s_cbranch_vccz .LBB0_1143
	s_barrier
